# s_setprio hints removed from the six GEMM phases (on top of v37)
# speedup vs baseline: 1.0021x; 1.0021x over previous
.LBB0_574:
	s_cmp_gt_u32 s63, 29
	s_cselect_b64 s[46:47], -1, 0
	ds_read_b128 v[160:163], v156
	ds_read_b128 v[164:167], v156 offset:1024
	ds_read_b128 v[168:171], v156 offset:2048
	ds_read_b128 v[172:175], v156 offset:3072
	ds_read_b128 v[176:179], v157
	ds_read_b128 v[180:183], v157 offset:1024
	ds_read_b128 v[184:187], v157 offset:2048
	ds_read_b128 v[188:191], v157 offset:3072
	s_and_b64 vcc, s[46:47], exec
	s_cselect_b32 s42, 0xffffffe2, 2
	s_add_i32 s46, s42, s63
	s_ashr_i32 s47, s46, 31
	s_lshl_b64 s[46:47], s[46:47], 7
	s_add_u32 s42, s50, s46
	s_addc_u32 s43, s51, s47
	s_add_u32 s46, s34, s46
	s_addc_u32 s47, s35, s47
	s_cmp_eq_u32 s63, 30
	s_cselect_b32 s53, s25, s43
	s_cselect_b32 s52, s61, s42
	s_cselect_b32 s47, s23, s47
	s_cselect_b32 s46, s62, s46
	s_add_i32 m0, s31, 0xc000
	ds_read_b128 v[192:195], v158
	ds_read_b128 v[196:199], v158 offset:1024
	ds_read_b128 v[200:203], v158 offset:2048
	ds_read_b128 v[204:207], v158 offset:3072
	ds_read_b128 v[208:211], v158 offset:4096
	ds_read_b128 v[212:215], v158 offset:5120
	ds_read_b128 v[216:219], v158 offset:6144
	ds_read_b128 v[220:223], v158 offset:7168
	global_load_lds_dwordx4 v[144:145], off
	s_add_i32 m0, s31, 0xe000
	s_nop 0
	global_load_lds_dwordx4 v[146:147], off
	s_waitcnt vmcnt(8)
	s_waitcnt lgkmcnt(0)
	s_barrier
	s_waitcnt lgkmcnt(0)
	v_mfma_f32_16x16x32_bf16 v[124:127], v[160:163], v[192:195], v[124:127]
	v_mfma_f32_16x16x32_bf16 v[120:123], v[168:171], v[192:195], v[120:123]
	v_mfma_f32_16x16x32_bf16 v[108:111], v[160:163], v[200:203], v[108:111]
	v_mfma_f32_16x16x32_bf16 v[104:107], v[168:171], v[200:203], v[104:107]
	v_mfma_f32_16x16x32_bf16 v[92:95], v[160:163], v[208:211], v[92:95]
	v_mfma_f32_16x16x32_bf16 v[88:91], v[168:171], v[208:211], v[88:91]
	v_mfma_f32_16x16x32_bf16 v[76:79], v[160:163], v[216:219], v[76:79]
	v_mfma_f32_16x16x32_bf16 v[72:75], v[168:171], v[216:219], v[72:75]
	v_mfma_f32_16x16x32_bf16 v[124:127], v[164:167], v[196:199], v[124:127]
	v_mfma_f32_16x16x32_bf16 v[120:123], v[172:175], v[196:199], v[120:123]
	v_mfma_f32_16x16x32_bf16 v[108:111], v[164:167], v[204:207], v[108:111]
	v_mfma_f32_16x16x32_bf16 v[104:107], v[172:175], v[204:207], v[104:107]
	v_mfma_f32_16x16x32_bf16 v[92:95], v[164:167], v[212:215], v[92:95]
	v_mfma_f32_16x16x32_bf16 v[88:91], v[172:175], v[212:215], v[88:91]
	v_mfma_f32_16x16x32_bf16 v[76:79], v[164:167], v[220:223], v[76:79]
	v_mfma_f32_16x16x32_bf16 v[72:75], v[172:175], v[220:223], v[72:75]
	v_mfma_f32_16x16x32_bf16 v[116:119], v[176:179], v[192:195], v[116:119]
	v_mfma_f32_16x16x32_bf16 v[112:115], v[184:187], v[192:195], v[112:115]
	v_mfma_f32_16x16x32_bf16 v[100:103], v[176:179], v[200:203], v[100:103]
	v_mfma_f32_16x16x32_bf16 v[96:99], v[184:187], v[200:203], v[96:99]
	v_mfma_f32_16x16x32_bf16 v[84:87], v[176:179], v[208:211], v[84:87]
	v_mfma_f32_16x16x32_bf16 v[80:83], v[184:187], v[208:211], v[80:83]
	v_mfma_f32_16x16x32_bf16 v[68:71], v[176:179], v[216:219], v[68:71]
	v_mfma_f32_16x16x32_bf16 v[64:67], v[184:187], v[216:219], v[64:67]
	v_mfma_f32_16x16x32_bf16 v[116:119], v[180:183], v[196:199], v[116:119]
	v_mfma_f32_16x16x32_bf16 v[112:115], v[188:191], v[196:199], v[112:115]
	v_mfma_f32_16x16x32_bf16 v[100:103], v[180:183], v[204:207], v[100:103]
	v_mfma_f32_16x16x32_bf16 v[96:99], v[188:191], v[204:207], v[96:99]
	v_mfma_f32_16x16x32_bf16 v[84:87], v[180:183], v[212:215], v[84:87]
	v_mfma_f32_16x16x32_bf16 v[80:83], v[188:191], v[212:215], v[80:83]
	v_mfma_f32_16x16x32_bf16 v[68:71], v[180:183], v[220:223], v[68:71]
	v_mfma_f32_16x16x32_bf16 v[64:67], v[188:191], v[220:223], v[64:67]
	s_barrier
	s_add_i32 s42, s57, s39
	v_lshl_add_u64 v[148:149], s[46:47], 0, v[130:131]
	s_mov_b32 m0, s42
	ds_read_b128 v[192:195], v158 offset:16384
	ds_read_b128 v[196:199], v158 offset:17408
	ds_read_b128 v[200:203], v158 offset:18432
	ds_read_b128 v[204:207], v158 offset:19456
	ds_read_b128 v[208:211], v158 offset:20480
	ds_read_b128 v[212:215], v158 offset:21504
	ds_read_b128 v[216:219], v158 offset:22528
	ds_read_b128 v[220:223], v158 offset:23552
	global_load_lds_dwordx4 v[148:149], off
	s_add_i32 m0, s42, 0x2000
	s_add_u32 s64, s46, 0x80000
	v_lshl_add_u64 v[224:225], s[46:47], 0, v[134:135]
	s_addc_u32 s65, s47, 0
	s_add_i32 s42, s58, s39
	global_load_lds_dwordx4 v[224:225], off
	v_lshl_add_u64 v[226:227], s[64:65], 0, v[130:131]
	s_mov_b32 m0, s42
	v_lshl_add_u64 v[228:229], s[52:53], 0, v[132:133]
	global_load_lds_dwordx4 v[226:227], off
	v_lshl_add_u64 v[226:227], s[64:65], 0, v[134:135]
	s_add_i32 m0, s42, 0x2000
	s_nop 0
	global_load_lds_dwordx4 v[226:227], off
	v_lshl_add_u64 v[226:227], s[52:53], 0, v[128:129]
	s_mov_b32 m0, s31
	s_nop 0
	global_load_lds_dwordx4 v[226:227], off
	s_mov_b32 m0, s44
	s_nop 0
	global_load_lds_dwordx4 v[228:229], off
	s_waitcnt vmcnt(8)
	s_waitcnt lgkmcnt(0)
	s_barrier
	s_waitcnt lgkmcnt(0)
	v_mfma_f32_16x16x32_bf16 v[60:63], v[160:163], v[192:195], v[60:63]
	v_mfma_f32_16x16x32_bf16 v[56:59], v[168:171], v[192:195], v[56:59]
	v_mfma_f32_16x16x32_bf16 v[44:47], v[160:163], v[200:203], v[44:47]
	v_mfma_f32_16x16x32_bf16 v[40:43], v[168:171], v[200:203], v[40:43]
	v_mfma_f32_16x16x32_bf16 v[28:31], v[160:163], v[208:211], v[28:31]
	v_mfma_f32_16x16x32_bf16 v[24:27], v[168:171], v[208:211], v[24:27]
	v_mfma_f32_16x16x32_bf16 v[12:15], v[160:163], v[216:219], v[12:15]
	v_mfma_f32_16x16x32_bf16 v[8:11], v[168:171], v[216:219], v[8:11]
	v_mfma_f32_16x16x32_bf16 v[60:63], v[164:167], v[196:199], v[60:63]
	v_mfma_f32_16x16x32_bf16 v[56:59], v[172:175], v[196:199], v[56:59]
	v_mfma_f32_16x16x32_bf16 v[44:47], v[164:167], v[204:207], v[44:47]
	v_mfma_f32_16x16x32_bf16 v[40:43], v[172:175], v[204:207], v[40:43]
	v_mfma_f32_16x16x32_bf16 v[28:31], v[164:167], v[212:215], v[28:31]
	v_mfma_f32_16x16x32_bf16 v[24:27], v[172:175], v[212:215], v[24:27]
	v_mfma_f32_16x16x32_bf16 v[12:15], v[164:167], v[220:223], v[12:15]
	v_mfma_f32_16x16x32_bf16 v[8:11], v[172:175], v[220:223], v[8:11]
	v_mfma_f32_16x16x32_bf16 v[52:55], v[176:179], v[192:195], v[52:55]
	v_mfma_f32_16x16x32_bf16 v[48:51], v[184:187], v[192:195], v[48:51]
	v_mfma_f32_16x16x32_bf16 v[36:39], v[176:179], v[200:203], v[36:39]
	v_mfma_f32_16x16x32_bf16 v[32:35], v[184:187], v[200:203], v[32:35]
	v_mfma_f32_16x16x32_bf16 v[20:23], v[176:179], v[208:211], v[20:23]
	v_mfma_f32_16x16x32_bf16 v[16:19], v[184:187], v[208:211], v[16:19]
	v_mfma_f32_16x16x32_bf16 v[4:7], v[176:179], v[216:219], v[4:7]
	v_mfma_f32_16x16x32_bf16 v[0:3], v[184:187], v[216:219], v[0:3]
	v_mfma_f32_16x16x32_bf16 v[52:55], v[180:183], v[196:199], v[52:55]
	v_mfma_f32_16x16x32_bf16 v[48:51], v[188:191], v[196:199], v[48:51]
	v_mfma_f32_16x16x32_bf16 v[36:39], v[180:183], v[204:207], v[36:39]
	v_mfma_f32_16x16x32_bf16 v[32:35], v[188:191], v[204:207], v[32:35]
	v_mfma_f32_16x16x32_bf16 v[20:23], v[180:183], v[212:215], v[20:23]
	v_mfma_f32_16x16x32_bf16 v[16:19], v[188:191], v[212:215], v[16:19]
	v_mfma_f32_16x16x32_bf16 v[4:7], v[180:183], v[220:223], v[4:7]
	v_mfma_f32_16x16x32_bf16 v[0:3], v[188:191], v[220:223], v[0:3]
	s_barrier
	s_add_i32 s42, 0, 0x18000
	v_add_u32_e32 v159, s42, v151
	s_add_i32 s43, 0, 0x1c000
	ds_read_b128 v[160:163], v159
	ds_read_b128 v[164:167], v159 offset:1024
	ds_read_b128 v[168:171], v159 offset:2048
	ds_read_b128 v[172:175], v159 offset:3072
	v_add_u32_e32 v159, s43, v151
	ds_read_b128 v[176:179], v159
	ds_read_b128 v[180:183], v159 offset:1024
	ds_read_b128 v[184:187], v159 offset:2048
	ds_read_b128 v[188:191], v159 offset:3072
	s_add_u32 s52, s52, 0x80000
	s_addc_u32 s53, s53, 0
	s_mov_b32 m0, s45
	v_lshl_add_u64 v[230:231], s[52:53], 0, v[128:129]
	ds_read_b128 v[192:195], v158 offset:32768
	ds_read_b128 v[196:199], v158 offset:33792
	ds_read_b128 v[200:203], v158 offset:34816
	ds_read_b128 v[204:207], v158 offset:35840
	ds_read_b128 v[208:211], v158 offset:36864
	ds_read_b128 v[212:215], v158 offset:37888
	ds_read_b128 v[216:219], v158 offset:38912
	ds_read_b128 v[220:223], v158 offset:39936
	global_load_lds_dwordx4 v[230:231], off
	v_lshl_add_u64 v[230:231], s[52:53], 0, v[132:133]
	s_mov_b32 m0, s48
	s_nop 0
	global_load_lds_dwordx4 v[230:231], off
	s_waitcnt vmcnt(8)
	s_waitcnt lgkmcnt(0)
	s_barrier
	s_waitcnt lgkmcnt(0)
	v_mfma_f32_16x16x32_bf16 v[124:127], v[160:163], v[192:195], v[124:127]
	v_mfma_f32_16x16x32_bf16 v[120:123], v[168:171], v[192:195], v[120:123]
	v_mfma_f32_16x16x32_bf16 v[108:111], v[160:163], v[200:203], v[108:111]
	v_mfma_f32_16x16x32_bf16 v[104:107], v[168:171], v[200:203], v[104:107]
	v_mfma_f32_16x16x32_bf16 v[92:95], v[160:163], v[208:211], v[92:95]
	v_mfma_f32_16x16x32_bf16 v[88:91], v[168:171], v[208:211], v[88:91]
	v_mfma_f32_16x16x32_bf16 v[76:79], v[160:163], v[216:219], v[76:79]
	v_mfma_f32_16x16x32_bf16 v[72:75], v[168:171], v[216:219], v[72:75]
	v_mfma_f32_16x16x32_bf16 v[124:127], v[164:167], v[196:199], v[124:127]
	v_mfma_f32_16x16x32_bf16 v[120:123], v[172:175], v[196:199], v[120:123]
	v_mfma_f32_16x16x32_bf16 v[108:111], v[164:167], v[204:207], v[108:111]
	v_mfma_f32_16x16x32_bf16 v[104:107], v[172:175], v[204:207], v[104:107]
	v_mfma_f32_16x16x32_bf16 v[92:95], v[164:167], v[212:215], v[92:95]
	v_mfma_f32_16x16x32_bf16 v[88:91], v[172:175], v[212:215], v[88:91]
	v_mfma_f32_16x16x32_bf16 v[76:79], v[164:167], v[220:223], v[76:79]
	v_mfma_f32_16x16x32_bf16 v[72:75], v[172:175], v[220:223], v[72:75]
	v_mfma_f32_16x16x32_bf16 v[116:119], v[176:179], v[192:195], v[116:119]
	v_mfma_f32_16x16x32_bf16 v[112:115], v[184:187], v[192:195], v[112:115]
	v_mfma_f32_16x16x32_bf16 v[100:103], v[176:179], v[200:203], v[100:103]
	v_mfma_f32_16x16x32_bf16 v[96:99], v[184:187], v[200:203], v[96:99]
	v_mfma_f32_16x16x32_bf16 v[84:87], v[176:179], v[208:211], v[84:87]
	v_mfma_f32_16x16x32_bf16 v[80:83], v[184:187], v[208:211], v[80:83]
	v_mfma_f32_16x16x32_bf16 v[68:71], v[176:179], v[216:219], v[68:71]
	v_mfma_f32_16x16x32_bf16 v[64:67], v[184:187], v[216:219], v[64:67]
	v_mfma_f32_16x16x32_bf16 v[116:119], v[180:183], v[196:199], v[116:119]
	v_mfma_f32_16x16x32_bf16 v[112:115], v[188:191], v[196:199], v[112:115]
	v_mfma_f32_16x16x32_bf16 v[100:103], v[180:183], v[204:207], v[100:103]
	v_mfma_f32_16x16x32_bf16 v[96:99], v[188:191], v[204:207], v[96:99]
	v_mfma_f32_16x16x32_bf16 v[84:87], v[180:183], v[212:215], v[84:87]
	v_mfma_f32_16x16x32_bf16 v[80:83], v[188:191], v[212:215], v[80:83]
	v_mfma_f32_16x16x32_bf16 v[68:71], v[180:183], v[220:223], v[68:71]
	v_mfma_f32_16x16x32_bf16 v[64:67], v[188:191], v[220:223], v[64:67]
	s_barrier
	s_add_i32 s42, s42, s39
	v_lshl_add_u64 v[148:149], v[148:149], 0, s[16:17]
	s_mov_b32 m0, s42
	ds_read_b128 v[192:195], v158 offset:49152
	ds_read_b128 v[196:199], v158 offset:50176
	ds_read_b128 v[200:203], v158 offset:51200
	ds_read_b128 v[204:207], v158 offset:52224
	ds_read_b128 v[208:211], v158 offset:53248
	ds_read_b128 v[212:215], v158 offset:54272
	ds_read_b128 v[216:219], v158 offset:55296
	ds_read_b128 v[220:223], v158 offset:56320
	global_load_lds_dwordx4 v[148:149], off
	s_add_i32 m0, s42, 0x2000
	s_add_u32 s46, s46, 0x80080
	v_lshl_add_u64 v[148:149], v[224:225], 0, s[16:17]
	s_addc_u32 s47, s47, 0
	s_add_i32 s42, s43, s39
	global_load_lds_dwordx4 v[148:149], off
	v_lshl_add_u64 v[148:149], s[46:47], 0, v[130:131]
	s_mov_b32 m0, s42
	s_nop 0
	global_load_lds_dwordx4 v[148:149], off
	v_lshl_add_u64 v[148:149], s[46:47], 0, v[134:135]
	s_add_i32 m0, s42, 0x2000
	s_nop 0
	global_load_lds_dwordx4 v[148:149], off
	v_lshl_add_u64 v[148:149], v[226:227], 0, s[16:17]
	s_mov_b32 m0, s54
	s_nop 0
	global_load_lds_dwordx4 v[148:149], off
	v_lshl_add_u64 v[148:149], v[228:229], 0, s[16:17]
	s_mov_b32 m0, s55
	s_nop 0
	global_load_lds_dwordx4 v[148:149], off
	s_waitcnt vmcnt(8)
	s_waitcnt lgkmcnt(0)
	s_barrier
	s_waitcnt lgkmcnt(0)
	v_mfma_f32_16x16x32_bf16 v[60:63], v[160:163], v[192:195], v[60:63]
	v_mfma_f32_16x16x32_bf16 v[56:59], v[168:171], v[192:195], v[56:59]
	v_mfma_f32_16x16x32_bf16 v[44:47], v[160:163], v[200:203], v[44:47]
	v_mfma_f32_16x16x32_bf16 v[40:43], v[168:171], v[200:203], v[40:43]
	v_mfma_f32_16x16x32_bf16 v[28:31], v[160:163], v[208:211], v[28:31]
	v_mfma_f32_16x16x32_bf16 v[24:27], v[168:171], v[208:211], v[24:27]
	v_mfma_f32_16x16x32_bf16 v[12:15], v[160:163], v[216:219], v[12:15]
	v_mfma_f32_16x16x32_bf16 v[8:11], v[168:171], v[216:219], v[8:11]
	v_mfma_f32_16x16x32_bf16 v[60:63], v[164:167], v[196:199], v[60:63]
	v_mfma_f32_16x16x32_bf16 v[56:59], v[172:175], v[196:199], v[56:59]
	v_mfma_f32_16x16x32_bf16 v[44:47], v[164:167], v[204:207], v[44:47]
	v_mfma_f32_16x16x32_bf16 v[40:43], v[172:175], v[204:207], v[40:43]
	v_mfma_f32_16x16x32_bf16 v[28:31], v[164:167], v[212:215], v[28:31]
	v_mfma_f32_16x16x32_bf16 v[24:27], v[172:175], v[212:215], v[24:27]
	v_mfma_f32_16x16x32_bf16 v[12:15], v[164:167], v[220:223], v[12:15]
	v_mfma_f32_16x16x32_bf16 v[8:11], v[172:175], v[220:223], v[8:11]
	v_mfma_f32_16x16x32_bf16 v[52:55], v[176:179], v[192:195], v[52:55]
	v_mfma_f32_16x16x32_bf16 v[48:51], v[184:187], v[192:195], v[48:51]
	v_mfma_f32_16x16x32_bf16 v[36:39], v[176:179], v[200:203], v[36:39]
	v_mfma_f32_16x16x32_bf16 v[32:35], v[184:187], v[200:203], v[32:35]
	v_mfma_f32_16x16x32_bf16 v[20:23], v[176:179], v[208:211], v[20:23]
	v_mfma_f32_16x16x32_bf16 v[16:19], v[184:187], v[208:211], v[16:19]
	v_mfma_f32_16x16x32_bf16 v[4:7], v[176:179], v[216:219], v[4:7]
	v_mfma_f32_16x16x32_bf16 v[0:3], v[184:187], v[216:219], v[0:3]
	v_mfma_f32_16x16x32_bf16 v[52:55], v[180:183], v[196:199], v[52:55]
	v_mfma_f32_16x16x32_bf16 v[48:51], v[188:191], v[196:199], v[48:51]
	v_mfma_f32_16x16x32_bf16 v[36:39], v[180:183], v[204:207], v[36:39]
	v_mfma_f32_16x16x32_bf16 v[32:35], v[188:191], v[204:207], v[32:35]
	v_mfma_f32_16x16x32_bf16 v[20:23], v[180:183], v[212:215], v[20:23]
	v_mfma_f32_16x16x32_bf16 v[16:19], v[188:191], v[212:215], v[16:19]
	v_mfma_f32_16x16x32_bf16 v[4:7], v[180:183], v[220:223], v[4:7]
	v_mfma_f32_16x16x32_bf16 v[0:3], v[188:191], v[220:223], v[0:3]
	s_barrier
	s_add_i32 s63, s63, 2
	v_lshl_add_u64 v[144:145], v[144:145], 0, s[20:21]
	v_lshl_add_u64 v[146:147], v[146:147], 0, s[20:21]
	s_cbranch_vccz .LBB0_574
	s_and_b64 vcc, exec, s[18:19]
	s_cbranch_vccz .LBB0_577
	s_barrier

.LBB0_665:
	s_add_i32 s26, s34, s61
	s_cmpk_lt_u32 s26, 0x58
	s_cselect_b32 s27, 0, 0xffffffa8
	s_add_i32 s28, s26, s27
	s_cmpk_lt_i32 s28, 0x56
	s_cselect_b32 s29, 0, 0xffffffa8
	ds_read_b128 v[140:143], v147
	ds_read_b128 v[150:153], v147 offset:1024
	ds_read_b128 v[154:157], v147 offset:2048
	ds_read_b128 v[158:161], v147 offset:3072
	ds_read_b128 v[162:165], v148
	ds_read_b128 v[166:169], v148 offset:1024
	ds_read_b128 v[170:173], v148 offset:2048
	ds_read_b128 v[174:177], v148 offset:3072
	s_add_i32 s27, s27, s29
	s_add_i32 s26, s26, s27
	s_add_i32 s26, s26, 2
	s_add_i32 s62, s28, 1
	s_ashr_i32 s27, s26, 31
	s_ashr_i32 s63, s62, 31
	s_lshl_b64 s[26:27], s[26:27], 7
	s_add_u32 s28, s24, s26
	s_addc_u32 s29, s25, s27
	s_add_u32 s26, s22, s26
	s_addc_u32 s27, s23, s27
	s_cmpk_eq_i32 s61, 0x56
	s_cselect_b32 s29, s58, s29
	s_cselect_b32 s28, s57, s28
	s_cselect_b32 s27, s60, s27
	s_cselect_b32 s26, s59, s26
	s_lshl_b64 s[62:63], s[62:63], 7
	s_add_u32 s62, s55, s62
	s_addc_u32 s63, s56, s63
	v_lshl_add_u64 v[210:211], s[62:63], 0, v[128:129]
	s_add_i32 m0, s39, 0xc000
	ds_read_b128 v[178:181], v149
	ds_read_b128 v[182:185], v149 offset:1024
	ds_read_b128 v[186:189], v149 offset:2048
	ds_read_b128 v[190:193], v149 offset:3072
	ds_read_b128 v[194:197], v149 offset:4096
	ds_read_b128 v[198:201], v149 offset:5120
	ds_read_b128 v[202:205], v149 offset:6144
	ds_read_b128 v[206:209], v149 offset:7168
	global_load_lds_dwordx4 v[210:211], off
	v_lshl_add_u64 v[210:211], s[62:63], 0, v[132:133]
	s_add_i32 m0, s39, 0xe000
	s_nop 0
	global_load_lds_dwordx4 v[210:211], off
	s_waitcnt vmcnt(8)
	s_waitcnt lgkmcnt(0)
	s_barrier
	s_waitcnt lgkmcnt(0)
	v_mfma_f32_16x16x32_bf16 v[124:127], v[140:143], v[178:181], v[124:127]
	v_mfma_f32_16x16x32_bf16 v[120:123], v[154:157], v[178:181], v[120:123]
	v_mfma_f32_16x16x32_bf16 v[116:119], v[140:143], v[186:189], v[116:119]
	v_mfma_f32_16x16x32_bf16 v[108:111], v[154:157], v[186:189], v[108:111]
	v_mfma_f32_16x16x32_bf16 v[100:103], v[140:143], v[194:197], v[100:103]
	v_mfma_f32_16x16x32_bf16 v[92:95], v[154:157], v[194:197], v[92:95]
	v_mfma_f32_16x16x32_bf16 v[84:87], v[140:143], v[202:205], v[84:87]
	v_mfma_f32_16x16x32_bf16 v[76:79], v[154:157], v[202:205], v[76:79]
	v_mfma_f32_16x16x32_bf16 v[124:127], v[150:153], v[182:185], v[124:127]
	v_mfma_f32_16x16x32_bf16 v[120:123], v[158:161], v[182:185], v[120:123]
	v_mfma_f32_16x16x32_bf16 v[116:119], v[150:153], v[190:193], v[116:119]
	v_mfma_f32_16x16x32_bf16 v[108:111], v[158:161], v[190:193], v[108:111]
	v_mfma_f32_16x16x32_bf16 v[100:103], v[150:153], v[198:201], v[100:103]
	v_mfma_f32_16x16x32_bf16 v[92:95], v[158:161], v[198:201], v[92:95]
	v_mfma_f32_16x16x32_bf16 v[84:87], v[150:153], v[206:209], v[84:87]
	v_mfma_f32_16x16x32_bf16 v[76:79], v[158:161], v[206:209], v[76:79]
	v_mfma_f32_16x16x32_bf16 v[112:115], v[162:165], v[178:181], v[112:115]
	v_mfma_f32_16x16x32_bf16 v[104:107], v[170:173], v[178:181], v[104:107]
	v_mfma_f32_16x16x32_bf16 v[96:99], v[162:165], v[186:189], v[96:99]
	v_mfma_f32_16x16x32_bf16 v[88:91], v[170:173], v[186:189], v[88:91]
	v_mfma_f32_16x16x32_bf16 v[80:83], v[162:165], v[194:197], v[80:83]
	v_mfma_f32_16x16x32_bf16 v[72:75], v[170:173], v[194:197], v[72:75]
	v_mfma_f32_16x16x32_bf16 v[68:71], v[162:165], v[202:205], v[68:71]
	v_mfma_f32_16x16x32_bf16 v[64:67], v[170:173], v[202:205], v[64:67]
	v_mfma_f32_16x16x32_bf16 v[112:115], v[166:169], v[182:185], v[112:115]
	v_mfma_f32_16x16x32_bf16 v[104:107], v[174:177], v[182:185], v[104:107]
	v_mfma_f32_16x16x32_bf16 v[96:99], v[166:169], v[190:193], v[96:99]
	v_mfma_f32_16x16x32_bf16 v[88:91], v[174:177], v[190:193], v[88:91]
	v_mfma_f32_16x16x32_bf16 v[80:83], v[166:169], v[198:201], v[80:83]
	v_mfma_f32_16x16x32_bf16 v[72:75], v[174:177], v[198:201], v[72:75]
	v_mfma_f32_16x16x32_bf16 v[68:71], v[166:169], v[206:209], v[68:71]
	v_mfma_f32_16x16x32_bf16 v[64:67], v[174:177], v[206:209], v[64:67]
	s_barrier
	s_add_i32 s42, s49, s35
	v_lshl_add_u64 v[210:211], s[26:27], 0, v[130:131]
	s_mov_b32 m0, s42
	ds_read_b128 v[178:181], v149 offset:16384
	ds_read_b128 v[182:185], v149 offset:17408
	ds_read_b128 v[186:189], v149 offset:18432
	ds_read_b128 v[190:193], v149 offset:19456
	ds_read_b128 v[194:197], v149 offset:20480
	ds_read_b128 v[198:201], v149 offset:21504
	ds_read_b128 v[202:205], v149 offset:22528
	ds_read_b128 v[206:209], v149 offset:23552
	global_load_lds_dwordx4 v[210:211], off
	s_add_i32 m0, s42, 0x2000
	s_add_u32 s62, s26, 0x160000
	v_lshl_add_u64 v[212:213], s[26:27], 0, v[134:135]
	s_addc_u32 s63, s27, 0
	s_add_i32 s42, s50, s35
	global_load_lds_dwordx4 v[212:213], off
	v_lshl_add_u64 v[214:215], s[62:63], 0, v[130:131]
	s_mov_b32 m0, s42
	v_lshl_add_u64 v[216:217], s[28:29], 0, v[132:133]
	global_load_lds_dwordx4 v[214:215], off
	v_lshl_add_u64 v[214:215], s[62:63], 0, v[134:135]
	s_add_i32 m0, s42, 0x2000
	s_nop 0
	global_load_lds_dwordx4 v[214:215], off
	v_lshl_add_u64 v[214:215], s[28:29], 0, v[128:129]
	s_mov_b32 m0, s39
	s_nop 0
	global_load_lds_dwordx4 v[214:215], off
	s_mov_b32 m0, s40
	s_nop 0
	global_load_lds_dwordx4 v[216:217], off
	s_waitcnt vmcnt(8)
	s_waitcnt lgkmcnt(0)
	s_barrier
	s_waitcnt lgkmcnt(0)
	v_mfma_f32_16x16x32_bf16 v[60:63], v[140:143], v[178:181], v[60:63]
	v_mfma_f32_16x16x32_bf16 v[56:59], v[154:157], v[178:181], v[56:59]
	v_mfma_f32_16x16x32_bf16 v[52:55], v[140:143], v[186:189], v[52:55]
	v_mfma_f32_16x16x32_bf16 v[44:47], v[154:157], v[186:189], v[44:47]
	v_mfma_f32_16x16x32_bf16 v[36:39], v[140:143], v[194:197], v[36:39]
	v_mfma_f32_16x16x32_bf16 v[28:31], v[154:157], v[194:197], v[28:31]
	v_mfma_f32_16x16x32_bf16 v[20:23], v[140:143], v[202:205], v[20:23]
	v_mfma_f32_16x16x32_bf16 v[12:15], v[154:157], v[202:205], v[12:15]
	v_mfma_f32_16x16x32_bf16 v[60:63], v[150:153], v[182:185], v[60:63]
	v_mfma_f32_16x16x32_bf16 v[56:59], v[158:161], v[182:185], v[56:59]
	v_mfma_f32_16x16x32_bf16 v[52:55], v[150:153], v[190:193], v[52:55]
	v_mfma_f32_16x16x32_bf16 v[44:47], v[158:161], v[190:193], v[44:47]
	v_mfma_f32_16x16x32_bf16 v[36:39], v[150:153], v[198:201], v[36:39]
	v_mfma_f32_16x16x32_bf16 v[28:31], v[158:161], v[198:201], v[28:31]
	v_mfma_f32_16x16x32_bf16 v[20:23], v[150:153], v[206:209], v[20:23]
	v_mfma_f32_16x16x32_bf16 v[12:15], v[158:161], v[206:209], v[12:15]
	v_mfma_f32_16x16x32_bf16 v[48:51], v[162:165], v[178:181], v[48:51]
	v_mfma_f32_16x16x32_bf16 v[40:43], v[170:173], v[178:181], v[40:43]
	v_mfma_f32_16x16x32_bf16 v[32:35], v[162:165], v[186:189], v[32:35]
	v_mfma_f32_16x16x32_bf16 v[24:27], v[170:173], v[186:189], v[24:27]
	v_mfma_f32_16x16x32_bf16 v[16:19], v[162:165], v[194:197], v[16:19]
	v_mfma_f32_16x16x32_bf16 v[8:11], v[170:173], v[194:197], v[8:11]
	v_mfma_f32_16x16x32_bf16 v[4:7], v[162:165], v[202:205], v[4:7]
	v_mfma_f32_16x16x32_bf16 v[0:3], v[170:173], v[202:205], v[0:3]
	v_mfma_f32_16x16x32_bf16 v[48:51], v[166:169], v[182:185], v[48:51]
	v_mfma_f32_16x16x32_bf16 v[40:43], v[174:177], v[182:185], v[40:43]
	v_mfma_f32_16x16x32_bf16 v[32:35], v[166:169], v[190:193], v[32:35]
	v_mfma_f32_16x16x32_bf16 v[24:27], v[174:177], v[190:193], v[24:27]
	v_mfma_f32_16x16x32_bf16 v[16:19], v[166:169], v[198:201], v[16:19]
	v_mfma_f32_16x16x32_bf16 v[8:11], v[174:177], v[198:201], v[8:11]
	v_mfma_f32_16x16x32_bf16 v[4:7], v[166:169], v[206:209], v[4:7]
	v_mfma_f32_16x16x32_bf16 v[0:3], v[174:177], v[206:209], v[0:3]
	s_barrier
	s_add_i32 s42, 0, 0x18000
	s_add_i32 s43, 0, 0x1c000
	v_add_u32_e32 v158, s42, v145
	v_add_u32_e32 v174, s43, v145
	ds_read_b128 v[140:143], v158
	ds_read_b128 v[150:153], v158 offset:1024
	ds_read_b128 v[154:157], v158 offset:2048
	ds_read_b128 v[158:161], v158 offset:3072
	ds_read_b128 v[162:165], v174
	ds_read_b128 v[166:169], v174 offset:1024
	ds_read_b128 v[170:173], v174 offset:2048
	ds_read_b128 v[174:177], v174 offset:3072
	s_add_u32 s28, s28, 0x160000
	s_addc_u32 s29, s29, 0
	s_mov_b32 m0, s41
	v_lshl_add_u64 v[218:219], s[28:29], 0, v[128:129]
	ds_read_b128 v[178:181], v149 offset:32768
	ds_read_b128 v[182:185], v149 offset:33792
	ds_read_b128 v[186:189], v149 offset:34816
	ds_read_b128 v[190:193], v149 offset:35840
	ds_read_b128 v[194:197], v149 offset:36864
	ds_read_b128 v[198:201], v149 offset:37888
	ds_read_b128 v[202:205], v149 offset:38912
	ds_read_b128 v[206:209], v149 offset:39936
	global_load_lds_dwordx4 v[218:219], off
	v_lshl_add_u64 v[218:219], s[28:29], 0, v[132:133]
	s_mov_b32 m0, s44
	s_nop 0
	global_load_lds_dwordx4 v[218:219], off
	s_waitcnt vmcnt(8)
	s_waitcnt lgkmcnt(0)
	s_barrier
	s_waitcnt lgkmcnt(0)
	v_mfma_f32_16x16x32_bf16 v[124:127], v[140:143], v[178:181], v[124:127]
	v_mfma_f32_16x16x32_bf16 v[120:123], v[154:157], v[178:181], v[120:123]
	v_mfma_f32_16x16x32_bf16 v[116:119], v[140:143], v[186:189], v[116:119]
	v_mfma_f32_16x16x32_bf16 v[108:111], v[154:157], v[186:189], v[108:111]
	v_mfma_f32_16x16x32_bf16 v[100:103], v[140:143], v[194:197], v[100:103]
	v_mfma_f32_16x16x32_bf16 v[92:95], v[154:157], v[194:197], v[92:95]
	v_mfma_f32_16x16x32_bf16 v[84:87], v[140:143], v[202:205], v[84:87]
	v_mfma_f32_16x16x32_bf16 v[76:79], v[154:157], v[202:205], v[76:79]
	v_mfma_f32_16x16x32_bf16 v[124:127], v[150:153], v[182:185], v[124:127]
	v_mfma_f32_16x16x32_bf16 v[120:123], v[158:161], v[182:185], v[120:123]
	v_mfma_f32_16x16x32_bf16 v[116:119], v[150:153], v[190:193], v[116:119]
	v_mfma_f32_16x16x32_bf16 v[108:111], v[158:161], v[190:193], v[108:111]
	v_mfma_f32_16x16x32_bf16 v[100:103], v[150:153], v[198:201], v[100:103]
	v_mfma_f32_16x16x32_bf16 v[92:95], v[158:161], v[198:201], v[92:95]
	v_mfma_f32_16x16x32_bf16 v[84:87], v[150:153], v[206:209], v[84:87]
	v_mfma_f32_16x16x32_bf16 v[76:79], v[158:161], v[206:209], v[76:79]
	v_mfma_f32_16x16x32_bf16 v[112:115], v[162:165], v[178:181], v[112:115]
	v_mfma_f32_16x16x32_bf16 v[104:107], v[170:173], v[178:181], v[104:107]
	v_mfma_f32_16x16x32_bf16 v[96:99], v[162:165], v[186:189], v[96:99]
	v_mfma_f32_16x16x32_bf16 v[88:91], v[170:173], v[186:189], v[88:91]
	v_mfma_f32_16x16x32_bf16 v[80:83], v[162:165], v[194:197], v[80:83]
	v_mfma_f32_16x16x32_bf16 v[72:75], v[170:173], v[194:197], v[72:75]
	v_mfma_f32_16x16x32_bf16 v[68:71], v[162:165], v[202:205], v[68:71]
	v_mfma_f32_16x16x32_bf16 v[64:67], v[170:173], v[202:205], v[64:67]
	v_mfma_f32_16x16x32_bf16 v[112:115], v[166:169], v[182:185], v[112:115]
	v_mfma_f32_16x16x32_bf16 v[104:107], v[174:177], v[182:185], v[104:107]
	v_mfma_f32_16x16x32_bf16 v[96:99], v[166:169], v[190:193], v[96:99]
	v_mfma_f32_16x16x32_bf16 v[88:91], v[174:177], v[190:193], v[88:91]
	v_mfma_f32_16x16x32_bf16 v[80:83], v[166:169], v[198:201], v[80:83]
	v_mfma_f32_16x16x32_bf16 v[72:75], v[174:177], v[198:201], v[72:75]
	v_mfma_f32_16x16x32_bf16 v[68:71], v[166:169], v[206:209], v[68:71]
	v_mfma_f32_16x16x32_bf16 v[64:67], v[174:177], v[206:209], v[64:67]
	s_barrier
	s_add_i32 s28, s42, s35
	v_lshl_add_u64 v[210:211], v[210:211], 0, s[16:17]
	s_mov_b32 m0, s28
	ds_read_b128 v[178:181], v149 offset:49152
	ds_read_b128 v[182:185], v149 offset:50176
	ds_read_b128 v[186:189], v149 offset:51200
	ds_read_b128 v[190:193], v149 offset:52224
	ds_read_b128 v[194:197], v149 offset:53248
	ds_read_b128 v[198:201], v149 offset:54272
	ds_read_b128 v[202:205], v149 offset:55296
	ds_read_b128 v[206:209], v149 offset:56320
	global_load_lds_dwordx4 v[210:211], off
	s_add_i32 m0, s28, 0x2000
	s_add_u32 s26, s26, 0x160080
	v_lshl_add_u64 v[210:211], v[212:213], 0, s[16:17]
	s_addc_u32 s27, s27, 0
	s_add_i32 s28, s43, s35
	global_load_lds_dwordx4 v[210:211], off
	v_lshl_add_u64 v[210:211], s[26:27], 0, v[130:131]
	s_mov_b32 m0, s28
	s_nop 0
	global_load_lds_dwordx4 v[210:211], off
	v_lshl_add_u64 v[210:211], s[26:27], 0, v[134:135]
	s_add_i32 m0, s28, 0x2000
	s_nop 0
	global_load_lds_dwordx4 v[210:211], off
	v_lshl_add_u64 v[210:211], v[214:215], 0, s[16:17]
	s_mov_b32 m0, s46
	s_nop 0
	global_load_lds_dwordx4 v[210:211], off
	v_lshl_add_u64 v[210:211], v[216:217], 0, s[16:17]
	s_mov_b32 m0, s47
	s_nop 0
	global_load_lds_dwordx4 v[210:211], off
	s_waitcnt vmcnt(8)
	s_waitcnt lgkmcnt(0)
	s_barrier
	s_waitcnt lgkmcnt(0)
	v_mfma_f32_16x16x32_bf16 v[60:63], v[140:143], v[178:181], v[60:63]
	v_mfma_f32_16x16x32_bf16 v[56:59], v[154:157], v[178:181], v[56:59]
	v_mfma_f32_16x16x32_bf16 v[52:55], v[140:143], v[186:189], v[52:55]
	v_mfma_f32_16x16x32_bf16 v[44:47], v[154:157], v[186:189], v[44:47]
	v_mfma_f32_16x16x32_bf16 v[36:39], v[140:143], v[194:197], v[36:39]
	v_mfma_f32_16x16x32_bf16 v[28:31], v[154:157], v[194:197], v[28:31]
	v_mfma_f32_16x16x32_bf16 v[20:23], v[140:143], v[202:205], v[20:23]
	v_mfma_f32_16x16x32_bf16 v[12:15], v[154:157], v[202:205], v[12:15]
	v_mfma_f32_16x16x32_bf16 v[60:63], v[150:153], v[182:185], v[60:63]
	v_mfma_f32_16x16x32_bf16 v[56:59], v[158:161], v[182:185], v[56:59]
	v_mfma_f32_16x16x32_bf16 v[52:55], v[150:153], v[190:193], v[52:55]
	v_mfma_f32_16x16x32_bf16 v[44:47], v[158:161], v[190:193], v[44:47]
	v_mfma_f32_16x16x32_bf16 v[36:39], v[150:153], v[198:201], v[36:39]
	v_mfma_f32_16x16x32_bf16 v[28:31], v[158:161], v[198:201], v[28:31]
	v_mfma_f32_16x16x32_bf16 v[20:23], v[150:153], v[206:209], v[20:23]
	v_mfma_f32_16x16x32_bf16 v[12:15], v[158:161], v[206:209], v[12:15]
	v_mfma_f32_16x16x32_bf16 v[48:51], v[162:165], v[178:181], v[48:51]
	v_mfma_f32_16x16x32_bf16 v[40:43], v[170:173], v[178:181], v[40:43]
	v_mfma_f32_16x16x32_bf16 v[32:35], v[162:165], v[186:189], v[32:35]
	v_mfma_f32_16x16x32_bf16 v[24:27], v[170:173], v[186:189], v[24:27]
	v_mfma_f32_16x16x32_bf16 v[16:19], v[162:165], v[194:197], v[16:19]
	v_mfma_f32_16x16x32_bf16 v[8:11], v[170:173], v[194:197], v[8:11]
	v_mfma_f32_16x16x32_bf16 v[4:7], v[162:165], v[202:205], v[4:7]
	v_mfma_f32_16x16x32_bf16 v[0:3], v[170:173], v[202:205], v[0:3]
	v_mfma_f32_16x16x32_bf16 v[48:51], v[166:169], v[182:185], v[48:51]
	v_mfma_f32_16x16x32_bf16 v[40:43], v[174:177], v[182:185], v[40:43]
	v_mfma_f32_16x16x32_bf16 v[32:35], v[166:169], v[190:193], v[32:35]
	v_mfma_f32_16x16x32_bf16 v[24:27], v[174:177], v[190:193], v[24:27]
	v_mfma_f32_16x16x32_bf16 v[16:19], v[166:169], v[198:201], v[16:19]
	v_mfma_f32_16x16x32_bf16 v[8:11], v[174:177], v[198:201], v[8:11]
	v_mfma_f32_16x16x32_bf16 v[4:7], v[166:169], v[206:209], v[4:7]
	v_mfma_f32_16x16x32_bf16 v[0:3], v[174:177], v[206:209], v[0:3]
	s_barrier
	s_add_i32 s26, s61, 2
	s_cmpk_gt_u32 s61, 0x55
	s_mov_b32 s61, s26
	s_cbranch_scc0 .LBB0_665
	s_and_b64 vcc, exec, s[18:19]
	s_cbranch_vccz .LBB0_668
	s_barrier

.LBB0_812:
	s_cmp_gt_u32 s85, 29
	s_cselect_b64 s[4:5], -1, 0
	ds_read_b128 v[132:135], v169
	ds_read_b128 v[154:157], v169 offset:1024
	ds_read_b128 v[158:161], v169 offset:2048
	ds_read_b128 v[162:165], v169 offset:3072
	ds_read_b128 v[172:175], v170
	ds_read_b128 v[176:179], v170 offset:1024
	ds_read_b128 v[180:183], v170 offset:2048
	ds_read_b128 v[184:187], v170 offset:3072
	s_and_b64 vcc, s[4:5], exec
	s_cselect_b32 s4, 0xffffffe2, 2
	s_add_i32 s4, s4, s85
	s_ashr_i32 s5, s4, 31
	s_lshl_b64 s[4:5], s[4:5], 7
	s_add_u32 s42, s92, s4
	s_addc_u32 s43, s93, s5
	s_add_u32 s4, s6, s4
	s_addc_u32 s5, s7, s5
	s_cmp_eq_u32 s85, 30
	s_cselect_b32 s47, s9, s43
	s_cselect_b32 s46, s40, s42
	s_cselect_b32 s5, s41, s5
	s_cselect_b32 s4, s83, s4
	s_add_i32 m0, s72, 0xc000
	ds_read_b128 v[188:191], v171
	ds_read_b128 v[192:195], v171 offset:1024
	ds_read_b128 v[196:199], v171 offset:2048
	ds_read_b128 v[200:203], v171 offset:3072
	ds_read_b128 v[204:207], v171 offset:4096
	ds_read_b128 v[208:211], v171 offset:5120
	ds_read_b128 v[212:215], v171 offset:6144
	ds_read_b128 v[216:219], v171 offset:7168
	global_load_lds_dwordx4 v[128:129], off
	s_add_i32 m0, s72, 0xe000
	s_nop 0
	global_load_lds_dwordx4 v[130:131], off
	s_waitcnt vmcnt(8)
	s_waitcnt lgkmcnt(0)
	s_barrier
	s_waitcnt lgkmcnt(0)
	v_mfma_f32_16x16x32_bf16 v[124:127], v[132:135], v[188:191], v[124:127]
	v_mfma_f32_16x16x32_bf16 v[120:123], v[158:161], v[188:191], v[120:123]
	v_mfma_f32_16x16x32_bf16 v[108:111], v[132:135], v[196:199], v[108:111]
	v_mfma_f32_16x16x32_bf16 v[104:107], v[158:161], v[196:199], v[104:107]
	v_mfma_f32_16x16x32_bf16 v[92:95], v[132:135], v[204:207], v[92:95]
	v_mfma_f32_16x16x32_bf16 v[88:91], v[158:161], v[204:207], v[88:91]
	v_mfma_f32_16x16x32_bf16 v[76:79], v[132:135], v[212:215], v[76:79]
	v_mfma_f32_16x16x32_bf16 v[72:75], v[158:161], v[212:215], v[72:75]
	v_mfma_f32_16x16x32_bf16 v[124:127], v[154:157], v[192:195], v[124:127]
	v_mfma_f32_16x16x32_bf16 v[120:123], v[162:165], v[192:195], v[120:123]
	v_mfma_f32_16x16x32_bf16 v[108:111], v[154:157], v[200:203], v[108:111]
	v_mfma_f32_16x16x32_bf16 v[104:107], v[162:165], v[200:203], v[104:107]
	v_mfma_f32_16x16x32_bf16 v[92:95], v[154:157], v[208:211], v[92:95]
	v_mfma_f32_16x16x32_bf16 v[88:91], v[162:165], v[208:211], v[88:91]
	v_mfma_f32_16x16x32_bf16 v[76:79], v[154:157], v[216:219], v[76:79]
	v_mfma_f32_16x16x32_bf16 v[72:75], v[162:165], v[216:219], v[72:75]
	v_mfma_f32_16x16x32_bf16 v[116:119], v[172:175], v[188:191], v[116:119]
	v_mfma_f32_16x16x32_bf16 v[112:115], v[180:183], v[188:191], v[112:115]
	v_mfma_f32_16x16x32_bf16 v[100:103], v[172:175], v[196:199], v[100:103]
	v_mfma_f32_16x16x32_bf16 v[96:99], v[180:183], v[196:199], v[96:99]
	v_mfma_f32_16x16x32_bf16 v[84:87], v[172:175], v[204:207], v[84:87]
	v_mfma_f32_16x16x32_bf16 v[80:83], v[180:183], v[204:207], v[80:83]
	v_mfma_f32_16x16x32_bf16 v[68:71], v[172:175], v[212:215], v[68:71]
	v_mfma_f32_16x16x32_bf16 v[64:67], v[180:183], v[212:215], v[64:67]
	v_mfma_f32_16x16x32_bf16 v[116:119], v[176:179], v[192:195], v[116:119]
	v_mfma_f32_16x16x32_bf16 v[112:115], v[184:187], v[192:195], v[112:115]
	v_mfma_f32_16x16x32_bf16 v[100:103], v[176:179], v[200:203], v[100:103]
	v_mfma_f32_16x16x32_bf16 v[96:99], v[184:187], v[200:203], v[96:99]
	v_mfma_f32_16x16x32_bf16 v[84:87], v[176:179], v[208:211], v[84:87]
	v_mfma_f32_16x16x32_bf16 v[80:83], v[184:187], v[208:211], v[80:83]
	v_mfma_f32_16x16x32_bf16 v[68:71], v[176:179], v[216:219], v[68:71]
	v_mfma_f32_16x16x32_bf16 v[64:67], v[184:187], v[216:219], v[64:67]
	s_barrier
	s_add_i32 s42, s37, s71
	v_lshl_add_u64 v[220:221], s[4:5], 0, v[138:139]
	s_mov_b32 m0, s42
	ds_read_b128 v[188:191], v171 offset:16384
	ds_read_b128 v[192:195], v171 offset:17408
	ds_read_b128 v[196:199], v171 offset:18432
	ds_read_b128 v[200:203], v171 offset:19456
	ds_read_b128 v[204:207], v171 offset:20480
	ds_read_b128 v[208:211], v171 offset:21504
	ds_read_b128 v[212:215], v171 offset:22528
	ds_read_b128 v[216:219], v171 offset:23552
	global_load_lds_dwordx4 v[220:221], off
	s_add_i32 m0, s42, 0x2000
	s_add_u32 s94, s4, 0x80000
	v_lshl_add_u64 v[222:223], s[4:5], 0, v[142:143]
	s_addc_u32 s95, s5, 0
	s_add_i32 s42, s56, s71
	global_load_lds_dwordx4 v[222:223], off
	v_lshl_add_u64 v[224:225], s[94:95], 0, v[138:139]
	s_mov_b32 m0, s42
	v_lshl_add_u64 v[226:227], s[46:47], 0, v[140:141]
	global_load_lds_dwordx4 v[224:225], off
	v_lshl_add_u64 v[224:225], s[94:95], 0, v[142:143]
	s_add_i32 m0, s42, 0x2000
	s_nop 0
	global_load_lds_dwordx4 v[224:225], off
	v_lshl_add_u64 v[224:225], s[46:47], 0, v[136:137]
	s_mov_b32 m0, s72
	s_nop 0
	global_load_lds_dwordx4 v[224:225], off
	s_mov_b32 m0, s74
	s_nop 0
	global_load_lds_dwordx4 v[226:227], off
	s_waitcnt vmcnt(8)
	s_waitcnt lgkmcnt(0)
	s_barrier
	s_waitcnt lgkmcnt(0)
	v_mfma_f32_16x16x32_bf16 v[60:63], v[132:135], v[188:191], v[60:63]
	v_mfma_f32_16x16x32_bf16 v[56:59], v[158:161], v[188:191], v[56:59]
	v_mfma_f32_16x16x32_bf16 v[44:47], v[132:135], v[196:199], v[44:47]
	v_mfma_f32_16x16x32_bf16 v[40:43], v[158:161], v[196:199], v[40:43]
	v_mfma_f32_16x16x32_bf16 v[28:31], v[132:135], v[204:207], v[28:31]
	v_mfma_f32_16x16x32_bf16 v[24:27], v[158:161], v[204:207], v[24:27]
	v_mfma_f32_16x16x32_bf16 v[12:15], v[132:135], v[212:215], v[12:15]
	v_mfma_f32_16x16x32_bf16 v[8:11], v[158:161], v[212:215], v[8:11]
	v_mfma_f32_16x16x32_bf16 v[60:63], v[154:157], v[192:195], v[60:63]
	v_mfma_f32_16x16x32_bf16 v[56:59], v[162:165], v[192:195], v[56:59]
	v_mfma_f32_16x16x32_bf16 v[44:47], v[154:157], v[200:203], v[44:47]
	v_mfma_f32_16x16x32_bf16 v[40:43], v[162:165], v[200:203], v[40:43]
	v_mfma_f32_16x16x32_bf16 v[28:31], v[154:157], v[208:211], v[28:31]
	v_mfma_f32_16x16x32_bf16 v[24:27], v[162:165], v[208:211], v[24:27]
	v_mfma_f32_16x16x32_bf16 v[12:15], v[154:157], v[216:219], v[12:15]
	v_mfma_f32_16x16x32_bf16 v[8:11], v[162:165], v[216:219], v[8:11]
	v_mfma_f32_16x16x32_bf16 v[52:55], v[172:175], v[188:191], v[52:55]
	v_mfma_f32_16x16x32_bf16 v[48:51], v[180:183], v[188:191], v[48:51]
	v_mfma_f32_16x16x32_bf16 v[36:39], v[172:175], v[196:199], v[36:39]
	v_mfma_f32_16x16x32_bf16 v[32:35], v[180:183], v[196:199], v[32:35]
	v_mfma_f32_16x16x32_bf16 v[20:23], v[172:175], v[204:207], v[20:23]
	v_mfma_f32_16x16x32_bf16 v[16:19], v[180:183], v[204:207], v[16:19]
	v_mfma_f32_16x16x32_bf16 v[4:7], v[172:175], v[212:215], v[4:7]
	v_mfma_f32_16x16x32_bf16 v[0:3], v[180:183], v[212:215], v[0:3]
	v_mfma_f32_16x16x32_bf16 v[52:55], v[176:179], v[192:195], v[52:55]
	v_mfma_f32_16x16x32_bf16 v[48:51], v[184:187], v[192:195], v[48:51]
	v_mfma_f32_16x16x32_bf16 v[36:39], v[176:179], v[200:203], v[36:39]
	v_mfma_f32_16x16x32_bf16 v[32:35], v[184:187], v[200:203], v[32:35]
	v_mfma_f32_16x16x32_bf16 v[20:23], v[176:179], v[208:211], v[20:23]
	v_mfma_f32_16x16x32_bf16 v[16:19], v[184:187], v[208:211], v[16:19]
	v_mfma_f32_16x16x32_bf16 v[4:7], v[176:179], v[216:219], v[4:7]
	v_mfma_f32_16x16x32_bf16 v[0:3], v[184:187], v[216:219], v[0:3]
	s_barrier
	s_add_i32 s42, 0, 0x18000
	v_add_u32_e32 v144, s42, v167
	s_add_i32 s43, 0, 0x1c000
	ds_read_b128 v[132:135], v144
	ds_read_b128 v[154:157], v144 offset:1024
	ds_read_b128 v[158:161], v144 offset:2048
	ds_read_b128 v[162:165], v144 offset:3072
	v_add_u32_e32 v144, s43, v167
	ds_read_b128 v[172:175], v144
	ds_read_b128 v[176:179], v144 offset:1024
	ds_read_b128 v[180:183], v144 offset:2048
	ds_read_b128 v[184:187], v144 offset:3072
	s_add_u32 s46, s46, 0x80000
	s_addc_u32 s47, s47, 0
	s_mov_b32 m0, s44
	v_lshl_add_u64 v[228:229], s[46:47], 0, v[136:137]
	ds_read_b128 v[188:191], v171 offset:32768
	ds_read_b128 v[192:195], v171 offset:33792
	ds_read_b128 v[196:199], v171 offset:34816
	ds_read_b128 v[200:203], v171 offset:35840
	ds_read_b128 v[204:207], v171 offset:36864
	ds_read_b128 v[208:211], v171 offset:37888
	ds_read_b128 v[212:215], v171 offset:38912
	ds_read_b128 v[216:219], v171 offset:39936
	global_load_lds_dwordx4 v[228:229], off
	v_lshl_add_u64 v[228:229], s[46:47], 0, v[140:141]
	s_mov_b32 m0, s45
	s_nop 0
	global_load_lds_dwordx4 v[228:229], off
	s_waitcnt vmcnt(8)
	s_waitcnt lgkmcnt(0)
	s_barrier
	s_waitcnt lgkmcnt(0)
	v_mfma_f32_16x16x32_bf16 v[124:127], v[132:135], v[188:191], v[124:127]
	v_mfma_f32_16x16x32_bf16 v[120:123], v[158:161], v[188:191], v[120:123]
	v_mfma_f32_16x16x32_bf16 v[108:111], v[132:135], v[196:199], v[108:111]
	v_mfma_f32_16x16x32_bf16 v[104:107], v[158:161], v[196:199], v[104:107]
	v_mfma_f32_16x16x32_bf16 v[92:95], v[132:135], v[204:207], v[92:95]
	v_mfma_f32_16x16x32_bf16 v[88:91], v[158:161], v[204:207], v[88:91]
	v_mfma_f32_16x16x32_bf16 v[76:79], v[132:135], v[212:215], v[76:79]
	v_mfma_f32_16x16x32_bf16 v[72:75], v[158:161], v[212:215], v[72:75]
	v_mfma_f32_16x16x32_bf16 v[124:127], v[154:157], v[192:195], v[124:127]
	v_mfma_f32_16x16x32_bf16 v[120:123], v[162:165], v[192:195], v[120:123]
	v_mfma_f32_16x16x32_bf16 v[108:111], v[154:157], v[200:203], v[108:111]
	v_mfma_f32_16x16x32_bf16 v[104:107], v[162:165], v[200:203], v[104:107]
	v_mfma_f32_16x16x32_bf16 v[92:95], v[154:157], v[208:211], v[92:95]
	v_mfma_f32_16x16x32_bf16 v[88:91], v[162:165], v[208:211], v[88:91]
	v_mfma_f32_16x16x32_bf16 v[76:79], v[154:157], v[216:219], v[76:79]
	v_mfma_f32_16x16x32_bf16 v[72:75], v[162:165], v[216:219], v[72:75]
	v_mfma_f32_16x16x32_bf16 v[116:119], v[172:175], v[188:191], v[116:119]
	v_mfma_f32_16x16x32_bf16 v[112:115], v[180:183], v[188:191], v[112:115]
	v_mfma_f32_16x16x32_bf16 v[100:103], v[172:175], v[196:199], v[100:103]
	v_mfma_f32_16x16x32_bf16 v[96:99], v[180:183], v[196:199], v[96:99]
	v_mfma_f32_16x16x32_bf16 v[84:87], v[172:175], v[204:207], v[84:87]
	v_mfma_f32_16x16x32_bf16 v[80:83], v[180:183], v[204:207], v[80:83]
	v_mfma_f32_16x16x32_bf16 v[68:71], v[172:175], v[212:215], v[68:71]
	v_mfma_f32_16x16x32_bf16 v[64:67], v[180:183], v[212:215], v[64:67]
	v_mfma_f32_16x16x32_bf16 v[116:119], v[176:179], v[192:195], v[116:119]
	v_mfma_f32_16x16x32_bf16 v[112:115], v[184:187], v[192:195], v[112:115]
	v_mfma_f32_16x16x32_bf16 v[100:103], v[176:179], v[200:203], v[100:103]
	v_mfma_f32_16x16x32_bf16 v[96:99], v[184:187], v[200:203], v[96:99]
	v_mfma_f32_16x16x32_bf16 v[84:87], v[176:179], v[208:211], v[84:87]
	v_mfma_f32_16x16x32_bf16 v[80:83], v[184:187], v[208:211], v[80:83]
	v_mfma_f32_16x16x32_bf16 v[68:71], v[176:179], v[216:219], v[68:71]
	v_mfma_f32_16x16x32_bf16 v[64:67], v[184:187], v[216:219], v[64:67]
	s_barrier
	s_add_i32 s42, s42, s71
	v_lshl_add_u64 v[220:221], v[220:221], 0, s[34:35]
	s_mov_b32 m0, s42
	ds_read_b128 v[188:191], v171 offset:49152
	ds_read_b128 v[192:195], v171 offset:50176
	ds_read_b128 v[196:199], v171 offset:51200
	ds_read_b128 v[200:203], v171 offset:52224
	ds_read_b128 v[204:207], v171 offset:53248
	ds_read_b128 v[208:211], v171 offset:54272
	ds_read_b128 v[212:215], v171 offset:55296
	ds_read_b128 v[216:219], v171 offset:56320
	global_load_lds_dwordx4 v[220:221], off
	s_add_i32 m0, s42, 0x2000
	s_add_u32 s4, s4, 0x80080
	v_lshl_add_u64 v[220:221], v[222:223], 0, s[34:35]
	s_addc_u32 s5, s5, 0
	s_add_i32 s42, s43, s71
	global_load_lds_dwordx4 v[220:221], off
	v_lshl_add_u64 v[220:221], s[4:5], 0, v[138:139]
	s_mov_b32 m0, s42
	s_nop 0
	global_load_lds_dwordx4 v[220:221], off
	v_lshl_add_u64 v[220:221], s[4:5], 0, v[142:143]
	s_add_i32 m0, s42, 0x2000
	s_nop 0
	global_load_lds_dwordx4 v[220:221], off
	v_lshl_add_u64 v[220:221], v[224:225], 0, s[34:35]
	s_mov_b32 m0, s60
	s_nop 0
	global_load_lds_dwordx4 v[220:221], off
	v_lshl_add_u64 v[220:221], v[226:227], 0, s[34:35]
	s_mov_b32 m0, s61
	s_nop 0
	global_load_lds_dwordx4 v[220:221], off
	s_waitcnt vmcnt(8)
	s_waitcnt lgkmcnt(0)
	s_barrier
	s_waitcnt lgkmcnt(0)
	v_mfma_f32_16x16x32_bf16 v[60:63], v[132:135], v[188:191], v[60:63]
	v_mfma_f32_16x16x32_bf16 v[56:59], v[158:161], v[188:191], v[56:59]
	v_mfma_f32_16x16x32_bf16 v[44:47], v[132:135], v[196:199], v[44:47]
	v_mfma_f32_16x16x32_bf16 v[40:43], v[158:161], v[196:199], v[40:43]
	v_mfma_f32_16x16x32_bf16 v[28:31], v[132:135], v[204:207], v[28:31]
	v_mfma_f32_16x16x32_bf16 v[24:27], v[158:161], v[204:207], v[24:27]
	v_mfma_f32_16x16x32_bf16 v[12:15], v[132:135], v[212:215], v[12:15]
	v_mfma_f32_16x16x32_bf16 v[8:11], v[158:161], v[212:215], v[8:11]
	v_mfma_f32_16x16x32_bf16 v[60:63], v[154:157], v[192:195], v[60:63]
	v_mfma_f32_16x16x32_bf16 v[56:59], v[162:165], v[192:195], v[56:59]
	v_mfma_f32_16x16x32_bf16 v[44:47], v[154:157], v[200:203], v[44:47]
	v_mfma_f32_16x16x32_bf16 v[40:43], v[162:165], v[200:203], v[40:43]
	v_mfma_f32_16x16x32_bf16 v[28:31], v[154:157], v[208:211], v[28:31]
	v_mfma_f32_16x16x32_bf16 v[24:27], v[162:165], v[208:211], v[24:27]
	v_mfma_f32_16x16x32_bf16 v[12:15], v[154:157], v[216:219], v[12:15]
	v_mfma_f32_16x16x32_bf16 v[8:11], v[162:165], v[216:219], v[8:11]
	v_mfma_f32_16x16x32_bf16 v[52:55], v[172:175], v[188:191], v[52:55]
	v_mfma_f32_16x16x32_bf16 v[48:51], v[180:183], v[188:191], v[48:51]
	v_mfma_f32_16x16x32_bf16 v[36:39], v[172:175], v[196:199], v[36:39]
	v_mfma_f32_16x16x32_bf16 v[32:35], v[180:183], v[196:199], v[32:35]
	v_mfma_f32_16x16x32_bf16 v[20:23], v[172:175], v[204:207], v[20:23]
	v_mfma_f32_16x16x32_bf16 v[16:19], v[180:183], v[204:207], v[16:19]
	v_mfma_f32_16x16x32_bf16 v[4:7], v[172:175], v[212:215], v[4:7]
	v_mfma_f32_16x16x32_bf16 v[0:3], v[180:183], v[212:215], v[0:3]
	v_mfma_f32_16x16x32_bf16 v[52:55], v[176:179], v[192:195], v[52:55]
	v_mfma_f32_16x16x32_bf16 v[48:51], v[184:187], v[192:195], v[48:51]
	v_mfma_f32_16x16x32_bf16 v[36:39], v[176:179], v[200:203], v[36:39]
	v_mfma_f32_16x16x32_bf16 v[32:35], v[184:187], v[200:203], v[32:35]
	v_mfma_f32_16x16x32_bf16 v[20:23], v[176:179], v[208:211], v[20:23]
	v_mfma_f32_16x16x32_bf16 v[16:19], v[184:187], v[208:211], v[16:19]
	v_mfma_f32_16x16x32_bf16 v[4:7], v[176:179], v[216:219], v[4:7]
	v_mfma_f32_16x16x32_bf16 v[0:3], v[184:187], v[216:219], v[0:3]
	s_barrier
	s_add_i32 s85, s85, 2
	v_lshl_add_u64 v[128:129], v[128:129], 0, s[58:59]
	v_lshl_add_u64 v[130:131], v[130:131], 0, s[58:59]
	s_cbranch_vccz .LBB0_812
	s_and_b64 vcc, exec, s[50:51]
	s_cbranch_vccz .LBB0_815
	s_barrier

.LBB0_2230:
	s_add_i32 s66, s65, 2
	s_cmp_lt_u32 s65, 30
	s_cselect_b32 s42, 0, 0xffffffe0
	s_add_i32 s42, s66, s42
	s_ashr_i32 s43, s42, 31
	s_lshl_b64 s[42:43], s[42:43], 7
	s_add_u32 s46, s34, s42
	s_addc_u32 s47, s35, s43
	s_add_u32 s42, s30, s42
	s_addc_u32 s43, s31, s43
	s_cmp_eq_u32 s65, 30
	s_cselect_b32 s53, s23, s47
	s_cselect_b32 s52, s63, s46
	s_cselect_b32 s55, s21, s43
	s_cselect_b32 s54, s64, s42
	s_add_i32 s43, s60, s40
	ds_read_b128 v[154:157], v151
	ds_read_b128 v[158:161], v151 offset:1024
	ds_read_b128 v[162:165], v151 offset:2048
	ds_read_b128 v[166:169], v151 offset:3072
	ds_read_b128 v[170:173], v152
	ds_read_b128 v[174:177], v152 offset:1024
	ds_read_b128 v[178:181], v152 offset:2048
	ds_read_b128 v[182:185], v152 offset:3072
	s_add_i32 m0, s29, 0xc000
	s_add_i32 s42, s29, 0xe000
	s_add_i32 s71, s43, 0x2000
	s_add_u32 s56, s54, 0x80000
	s_addc_u32 s57, s55, 0
	s_add_i32 s72, s61, s40
	s_add_i32 s74, s72, 0x2000
	s_add_i32 s75, 0, 0x18000
	s_add_i32 s76, 0, 0x1c000
	s_add_u32 s50, s52, 0x80000
	s_addc_u32 s51, s53, 0
	s_add_i32 s68, s75, s40
	s_add_i32 s67, s68, 0x2000
	s_add_u32 s46, s54, 0x80080
	s_addc_u32 s47, s55, 0
	s_add_i32 s70, s76, s40
	s_add_i32 s69, s70, 0x2000
	s_cmp_gt_u32 s65, 29
	ds_read_b128 v[186:189], v153
	ds_read_b128 v[190:193], v153 offset:1024
	ds_read_b128 v[194:197], v153 offset:2048
	ds_read_b128 v[198:201], v153 offset:3072
	ds_read_b128 v[202:205], v153 offset:4096
	ds_read_b128 v[206:209], v153 offset:5120
	ds_read_b128 v[210:213], v153 offset:6144
	ds_read_b128 v[214:217], v153 offset:7168
	global_load_lds_dwordx4 v[144:145], off
	s_mov_b32 m0, s42
	s_nop 0
	global_load_lds_dwordx4 v[146:147], off
	s_waitcnt vmcnt(8)
	s_waitcnt lgkmcnt(0)
	s_barrier
	s_waitcnt lgkmcnt(0)
	v_mfma_f32_16x16x32_bf16 v[124:127], v[154:157], v[186:189], v[124:127]
	v_mfma_f32_16x16x32_bf16 v[120:123], v[162:165], v[186:189], v[120:123]
	v_mfma_f32_16x16x32_bf16 v[116:119], v[154:157], v[194:197], v[116:119]
	v_mfma_f32_16x16x32_bf16 v[108:111], v[162:165], v[194:197], v[108:111]
	v_mfma_f32_16x16x32_bf16 v[100:103], v[154:157], v[202:205], v[100:103]
	v_mfma_f32_16x16x32_bf16 v[92:95], v[162:165], v[202:205], v[92:95]
	v_mfma_f32_16x16x32_bf16 v[84:87], v[154:157], v[210:213], v[84:87]
	v_mfma_f32_16x16x32_bf16 v[76:79], v[162:165], v[210:213], v[76:79]
	v_mfma_f32_16x16x32_bf16 v[124:127], v[158:161], v[190:193], v[124:127]
	v_mfma_f32_16x16x32_bf16 v[120:123], v[166:169], v[190:193], v[120:123]
	v_mfma_f32_16x16x32_bf16 v[116:119], v[158:161], v[198:201], v[116:119]
	v_mfma_f32_16x16x32_bf16 v[108:111], v[166:169], v[198:201], v[108:111]
	v_mfma_f32_16x16x32_bf16 v[100:103], v[158:161], v[206:209], v[100:103]
	v_mfma_f32_16x16x32_bf16 v[92:95], v[166:169], v[206:209], v[92:95]
	v_mfma_f32_16x16x32_bf16 v[84:87], v[158:161], v[214:217], v[84:87]
	v_mfma_f32_16x16x32_bf16 v[76:79], v[166:169], v[214:217], v[76:79]
	v_mfma_f32_16x16x32_bf16 v[112:115], v[170:173], v[186:189], v[112:115]
	v_mfma_f32_16x16x32_bf16 v[104:107], v[178:181], v[186:189], v[104:107]
	v_mfma_f32_16x16x32_bf16 v[96:99], v[170:173], v[194:197], v[96:99]
	v_mfma_f32_16x16x32_bf16 v[88:91], v[178:181], v[194:197], v[88:91]
	v_mfma_f32_16x16x32_bf16 v[80:83], v[170:173], v[202:205], v[80:83]
	v_mfma_f32_16x16x32_bf16 v[72:75], v[178:181], v[202:205], v[72:75]
	v_mfma_f32_16x16x32_bf16 v[68:71], v[170:173], v[210:213], v[68:71]
	v_mfma_f32_16x16x32_bf16 v[64:67], v[178:181], v[210:213], v[64:67]
	v_mfma_f32_16x16x32_bf16 v[112:115], v[174:177], v[190:193], v[112:115]
	v_mfma_f32_16x16x32_bf16 v[104:107], v[182:185], v[190:193], v[104:107]
	v_mfma_f32_16x16x32_bf16 v[96:99], v[174:177], v[198:201], v[96:99]
	v_mfma_f32_16x16x32_bf16 v[88:91], v[182:185], v[198:201], v[88:91]
	v_mfma_f32_16x16x32_bf16 v[80:83], v[174:177], v[206:209], v[80:83]
	v_mfma_f32_16x16x32_bf16 v[72:75], v[182:185], v[206:209], v[72:75]
	v_mfma_f32_16x16x32_bf16 v[68:71], v[174:177], v[214:217], v[68:71]
	v_mfma_f32_16x16x32_bf16 v[64:67], v[182:185], v[214:217], v[64:67]
	s_barrier
	s_mov_b32 m0, s43
	v_lshl_add_u64 v[218:219], s[54:55], 0, v[130:131]
	ds_read_b128 v[186:189], v153 offset:16384
	ds_read_b128 v[190:193], v153 offset:17408
	ds_read_b128 v[194:197], v153 offset:18432
	ds_read_b128 v[198:201], v153 offset:19456
	ds_read_b128 v[202:205], v153 offset:20480
	ds_read_b128 v[206:209], v153 offset:21504
	ds_read_b128 v[210:213], v153 offset:22528
	ds_read_b128 v[214:217], v153 offset:23552
	global_load_lds_dwordx4 v[218:219], off
	v_lshl_add_u64 v[220:221], s[54:55], 0, v[134:135]
	s_mov_b32 m0, s71
	v_lshl_add_u64 v[222:223], s[56:57], 0, v[130:131]
	global_load_lds_dwordx4 v[220:221], off
	s_mov_b32 m0, s72
	v_lshl_add_u64 v[224:225], s[52:53], 0, v[132:133]
	global_load_lds_dwordx4 v[222:223], off
	v_lshl_add_u64 v[222:223], s[56:57], 0, v[134:135]
	s_mov_b32 m0, s74
	s_nop 0
	global_load_lds_dwordx4 v[222:223], off
	v_lshl_add_u64 v[222:223], s[52:53], 0, v[128:129]
	s_mov_b32 m0, s29
	s_nop 0
	global_load_lds_dwordx4 v[222:223], off
	s_mov_b32 m0, s41
	s_nop 0
	global_load_lds_dwordx4 v[224:225], off
	s_waitcnt vmcnt(8)
	s_waitcnt lgkmcnt(0)
	s_barrier
	s_waitcnt lgkmcnt(0)
	v_mfma_f32_16x16x32_bf16 v[60:63], v[154:157], v[186:189], v[60:63]
	v_mfma_f32_16x16x32_bf16 v[56:59], v[162:165], v[186:189], v[56:59]
	v_mfma_f32_16x16x32_bf16 v[52:55], v[154:157], v[194:197], v[52:55]
	v_mfma_f32_16x16x32_bf16 v[44:47], v[162:165], v[194:197], v[44:47]
	v_mfma_f32_16x16x32_bf16 v[36:39], v[154:157], v[202:205], v[36:39]
	v_mfma_f32_16x16x32_bf16 v[28:31], v[162:165], v[202:205], v[28:31]
	v_mfma_f32_16x16x32_bf16 v[20:23], v[154:157], v[210:213], v[20:23]
	v_mfma_f32_16x16x32_bf16 v[12:15], v[162:165], v[210:213], v[12:15]
	v_mfma_f32_16x16x32_bf16 v[60:63], v[158:161], v[190:193], v[60:63]
	v_mfma_f32_16x16x32_bf16 v[56:59], v[166:169], v[190:193], v[56:59]
	v_mfma_f32_16x16x32_bf16 v[52:55], v[158:161], v[198:201], v[52:55]
	v_mfma_f32_16x16x32_bf16 v[44:47], v[166:169], v[198:201], v[44:47]
	v_mfma_f32_16x16x32_bf16 v[36:39], v[158:161], v[206:209], v[36:39]
	v_mfma_f32_16x16x32_bf16 v[28:31], v[166:169], v[206:209], v[28:31]
	v_mfma_f32_16x16x32_bf16 v[20:23], v[158:161], v[214:217], v[20:23]
	v_mfma_f32_16x16x32_bf16 v[12:15], v[166:169], v[214:217], v[12:15]
	v_mfma_f32_16x16x32_bf16 v[48:51], v[170:173], v[186:189], v[48:51]
	v_mfma_f32_16x16x32_bf16 v[40:43], v[178:181], v[186:189], v[40:43]
	v_mfma_f32_16x16x32_bf16 v[32:35], v[170:173], v[194:197], v[32:35]
	v_mfma_f32_16x16x32_bf16 v[24:27], v[178:181], v[194:197], v[24:27]
	v_mfma_f32_16x16x32_bf16 v[16:19], v[170:173], v[202:205], v[16:19]
	v_mfma_f32_16x16x32_bf16 v[8:11], v[178:181], v[202:205], v[8:11]
	v_mfma_f32_16x16x32_bf16 v[4:7], v[170:173], v[210:213], v[4:7]
	v_mfma_f32_16x16x32_bf16 v[0:3], v[178:181], v[210:213], v[0:3]
	v_mfma_f32_16x16x32_bf16 v[48:51], v[174:177], v[190:193], v[48:51]
	v_mfma_f32_16x16x32_bf16 v[40:43], v[182:185], v[190:193], v[40:43]
	v_mfma_f32_16x16x32_bf16 v[32:35], v[174:177], v[198:201], v[32:35]
	v_mfma_f32_16x16x32_bf16 v[24:27], v[182:185], v[198:201], v[24:27]
	v_mfma_f32_16x16x32_bf16 v[16:19], v[174:177], v[206:209], v[16:19]
	v_mfma_f32_16x16x32_bf16 v[8:11], v[182:185], v[206:209], v[8:11]
	v_mfma_f32_16x16x32_bf16 v[4:7], v[174:177], v[214:217], v[4:7]
	v_mfma_f32_16x16x32_bf16 v[0:3], v[182:185], v[214:217], v[0:3]
	s_barrier
	v_add_u32_e32 v166, s75, v149
	v_add_u32_e32 v182, s76, v149
	ds_read_b128 v[154:157], v166
	ds_read_b128 v[158:161], v166 offset:1024
	ds_read_b128 v[162:165], v166 offset:2048
	ds_read_b128 v[166:169], v166 offset:3072
	ds_read_b128 v[170:173], v182
	ds_read_b128 v[174:177], v182 offset:1024
	ds_read_b128 v[178:181], v182 offset:2048
	ds_read_b128 v[182:185], v182 offset:3072
	s_mov_b32 m0, s44
	v_lshl_add_u64 v[226:227], s[50:51], 0, v[128:129]
	ds_read_b128 v[186:189], v153 offset:32768
	ds_read_b128 v[190:193], v153 offset:33792
	ds_read_b128 v[194:197], v153 offset:34816
	ds_read_b128 v[198:201], v153 offset:35840
	ds_read_b128 v[202:205], v153 offset:36864
	ds_read_b128 v[206:209], v153 offset:37888
	ds_read_b128 v[210:213], v153 offset:38912
	ds_read_b128 v[214:217], v153 offset:39936
	global_load_lds_dwordx4 v[226:227], off
	v_lshl_add_u64 v[226:227], s[50:51], 0, v[132:133]
	s_mov_b32 m0, s45
	s_nop 0
	global_load_lds_dwordx4 v[226:227], off
	s_waitcnt vmcnt(8)
	s_waitcnt lgkmcnt(0)
	s_barrier
	s_waitcnt lgkmcnt(0)
	v_mfma_f32_16x16x32_bf16 v[124:127], v[154:157], v[186:189], v[124:127]
	v_mfma_f32_16x16x32_bf16 v[120:123], v[162:165], v[186:189], v[120:123]
	v_mfma_f32_16x16x32_bf16 v[116:119], v[154:157], v[194:197], v[116:119]
	v_mfma_f32_16x16x32_bf16 v[108:111], v[162:165], v[194:197], v[108:111]
	v_mfma_f32_16x16x32_bf16 v[100:103], v[154:157], v[202:205], v[100:103]
	v_mfma_f32_16x16x32_bf16 v[92:95], v[162:165], v[202:205], v[92:95]
	v_mfma_f32_16x16x32_bf16 v[84:87], v[154:157], v[210:213], v[84:87]
	v_mfma_f32_16x16x32_bf16 v[76:79], v[162:165], v[210:213], v[76:79]
	v_mfma_f32_16x16x32_bf16 v[124:127], v[158:161], v[190:193], v[124:127]
	v_mfma_f32_16x16x32_bf16 v[120:123], v[166:169], v[190:193], v[120:123]
	v_mfma_f32_16x16x32_bf16 v[116:119], v[158:161], v[198:201], v[116:119]
	v_mfma_f32_16x16x32_bf16 v[108:111], v[166:169], v[198:201], v[108:111]
	v_mfma_f32_16x16x32_bf16 v[100:103], v[158:161], v[206:209], v[100:103]
	v_mfma_f32_16x16x32_bf16 v[92:95], v[166:169], v[206:209], v[92:95]
	v_mfma_f32_16x16x32_bf16 v[84:87], v[158:161], v[214:217], v[84:87]
	v_mfma_f32_16x16x32_bf16 v[76:79], v[166:169], v[214:217], v[76:79]
	v_mfma_f32_16x16x32_bf16 v[112:115], v[170:173], v[186:189], v[112:115]
	v_mfma_f32_16x16x32_bf16 v[104:107], v[178:181], v[186:189], v[104:107]
	v_mfma_f32_16x16x32_bf16 v[96:99], v[170:173], v[194:197], v[96:99]
	v_mfma_f32_16x16x32_bf16 v[88:91], v[178:181], v[194:197], v[88:91]
	v_mfma_f32_16x16x32_bf16 v[80:83], v[170:173], v[202:205], v[80:83]
	v_mfma_f32_16x16x32_bf16 v[72:75], v[178:181], v[202:205], v[72:75]
	v_mfma_f32_16x16x32_bf16 v[68:71], v[170:173], v[210:213], v[68:71]
	v_mfma_f32_16x16x32_bf16 v[64:67], v[178:181], v[210:213], v[64:67]
	v_mfma_f32_16x16x32_bf16 v[112:115], v[174:177], v[190:193], v[112:115]
	v_mfma_f32_16x16x32_bf16 v[104:107], v[182:185], v[190:193], v[104:107]
	v_mfma_f32_16x16x32_bf16 v[96:99], v[174:177], v[198:201], v[96:99]
	v_mfma_f32_16x16x32_bf16 v[88:91], v[182:185], v[198:201], v[88:91]
	v_mfma_f32_16x16x32_bf16 v[80:83], v[174:177], v[206:209], v[80:83]
	v_mfma_f32_16x16x32_bf16 v[72:75], v[182:185], v[206:209], v[72:75]
	v_mfma_f32_16x16x32_bf16 v[68:71], v[174:177], v[214:217], v[68:71]
	v_mfma_f32_16x16x32_bf16 v[64:67], v[182:185], v[214:217], v[64:67]
	s_barrier
	s_mov_b32 m0, s68
	v_lshl_add_u64 v[218:219], v[218:219], 0, s[14:15]
	ds_read_b128 v[186:189], v153 offset:49152
	ds_read_b128 v[190:193], v153 offset:50176
	ds_read_b128 v[194:197], v153 offset:51200
	ds_read_b128 v[198:201], v153 offset:52224
	ds_read_b128 v[202:205], v153 offset:53248
	ds_read_b128 v[206:209], v153 offset:54272
	ds_read_b128 v[210:213], v153 offset:55296
	ds_read_b128 v[214:217], v153 offset:56320
	global_load_lds_dwordx4 v[218:219], off
	v_lshl_add_u64 v[218:219], v[220:221], 0, s[14:15]
	s_mov_b32 m0, s67
	s_nop 0
	global_load_lds_dwordx4 v[218:219], off
	v_lshl_add_u64 v[218:219], s[46:47], 0, v[130:131]
	s_mov_b32 m0, s70
	s_nop 0
	global_load_lds_dwordx4 v[218:219], off
	v_lshl_add_u64 v[218:219], s[46:47], 0, v[134:135]
	s_mov_b32 m0, s69
	s_nop 0
	global_load_lds_dwordx4 v[218:219], off
	v_lshl_add_u64 v[218:219], v[222:223], 0, s[14:15]
	s_mov_b32 m0, s49
	s_nop 0
	global_load_lds_dwordx4 v[218:219], off
	v_lshl_add_u64 v[218:219], v[224:225], 0, s[14:15]
	s_mov_b32 m0, s58
	s_nop 0
	global_load_lds_dwordx4 v[218:219], off
	s_waitcnt vmcnt(8)
	s_waitcnt lgkmcnt(0)
	s_barrier
	s_waitcnt lgkmcnt(0)
	v_mfma_f32_16x16x32_bf16 v[60:63], v[154:157], v[186:189], v[60:63]
	v_mfma_f32_16x16x32_bf16 v[56:59], v[162:165], v[186:189], v[56:59]
	v_mfma_f32_16x16x32_bf16 v[52:55], v[154:157], v[194:197], v[52:55]
	v_mfma_f32_16x16x32_bf16 v[44:47], v[162:165], v[194:197], v[44:47]
	v_mfma_f32_16x16x32_bf16 v[36:39], v[154:157], v[202:205], v[36:39]
	v_mfma_f32_16x16x32_bf16 v[28:31], v[162:165], v[202:205], v[28:31]
	v_mfma_f32_16x16x32_bf16 v[20:23], v[154:157], v[210:213], v[20:23]
	v_mfma_f32_16x16x32_bf16 v[12:15], v[162:165], v[210:213], v[12:15]
	v_mfma_f32_16x16x32_bf16 v[60:63], v[158:161], v[190:193], v[60:63]
	v_mfma_f32_16x16x32_bf16 v[56:59], v[166:169], v[190:193], v[56:59]
	v_mfma_f32_16x16x32_bf16 v[52:55], v[158:161], v[198:201], v[52:55]
	v_mfma_f32_16x16x32_bf16 v[44:47], v[166:169], v[198:201], v[44:47]
	v_mfma_f32_16x16x32_bf16 v[36:39], v[158:161], v[206:209], v[36:39]
	v_mfma_f32_16x16x32_bf16 v[28:31], v[166:169], v[206:209], v[28:31]
	v_mfma_f32_16x16x32_bf16 v[20:23], v[158:161], v[214:217], v[20:23]
	v_mfma_f32_16x16x32_bf16 v[12:15], v[166:169], v[214:217], v[12:15]
	v_mfma_f32_16x16x32_bf16 v[48:51], v[170:173], v[186:189], v[48:51]
	v_mfma_f32_16x16x32_bf16 v[40:43], v[178:181], v[186:189], v[40:43]
	v_mfma_f32_16x16x32_bf16 v[32:35], v[170:173], v[194:197], v[32:35]
	v_mfma_f32_16x16x32_bf16 v[24:27], v[178:181], v[194:197], v[24:27]
	v_mfma_f32_16x16x32_bf16 v[16:19], v[170:173], v[202:205], v[16:19]
	v_mfma_f32_16x16x32_bf16 v[8:11], v[178:181], v[202:205], v[8:11]
	v_mfma_f32_16x16x32_bf16 v[4:7], v[170:173], v[210:213], v[4:7]
	v_mfma_f32_16x16x32_bf16 v[0:3], v[178:181], v[210:213], v[0:3]
	v_mfma_f32_16x16x32_bf16 v[48:51], v[174:177], v[190:193], v[48:51]
	v_mfma_f32_16x16x32_bf16 v[40:43], v[182:185], v[190:193], v[40:43]
	v_mfma_f32_16x16x32_bf16 v[32:35], v[174:177], v[198:201], v[32:35]
	v_mfma_f32_16x16x32_bf16 v[24:27], v[182:185], v[198:201], v[24:27]
	v_mfma_f32_16x16x32_bf16 v[16:19], v[174:177], v[206:209], v[16:19]
	v_mfma_f32_16x16x32_bf16 v[8:11], v[182:185], v[206:209], v[8:11]
	v_mfma_f32_16x16x32_bf16 v[4:7], v[174:177], v[214:217], v[4:7]
	v_mfma_f32_16x16x32_bf16 v[0:3], v[182:185], v[214:217], v[0:3]
	s_barrier
	v_lshl_add_u64 v[144:145], v[144:145], 0, s[18:19]
	v_lshl_add_u64 v[146:147], v[146:147], 0, s[18:19]
	s_mov_b32 s65, s66
	s_cbranch_scc0 .LBB0_2230
	s_and_b64 vcc, exec, s[16:17]
	s_cbranch_vccz .LBB0_2233
	s_barrier

.LBB0_2375:
	s_cmp_gt_u32 s63, 29
	s_cselect_b64 s[42:43], -1, 0
	ds_read_b128 v[160:163], v156
	ds_read_b128 v[164:167], v156 offset:1024
	ds_read_b128 v[168:171], v156 offset:2048
	ds_read_b128 v[172:175], v156 offset:3072
	ds_read_b128 v[176:179], v157
	ds_read_b128 v[180:183], v157 offset:1024
	ds_read_b128 v[184:187], v157 offset:2048
	ds_read_b128 v[188:191], v157 offset:3072
	s_and_b64 vcc, s[42:43], exec
	s_cselect_b32 s42, 0xffffffe2, 2
	s_add_i32 s42, s42, s63
	s_ashr_i32 s43, s42, 31
	s_lshl_b64 s[42:43], s[42:43], 7
	s_add_u32 s46, s50, s42
	s_addc_u32 s47, s51, s43
	s_add_u32 s42, s34, s42
	s_addc_u32 s43, s35, s43
	s_cmp_eq_u32 s63, 30
	s_cselect_b32 s53, s25, s47
	s_cselect_b32 s52, s61, s46
	s_cselect_b32 s47, s23, s43
	s_cselect_b32 s46, s62, s42
	s_add_i32 m0, s31, 0xc000
	ds_read_b128 v[192:195], v158
	ds_read_b128 v[196:199], v158 offset:1024
	ds_read_b128 v[200:203], v158 offset:2048
	ds_read_b128 v[204:207], v158 offset:3072
	ds_read_b128 v[208:211], v158 offset:4096
	ds_read_b128 v[212:215], v158 offset:5120
	ds_read_b128 v[216:219], v158 offset:6144
	ds_read_b128 v[220:223], v158 offset:7168
	global_load_lds_dwordx4 v[144:145], off
	s_add_i32 m0, s31, 0xe000
	s_nop 0
	global_load_lds_dwordx4 v[146:147], off
	s_waitcnt vmcnt(8)
	s_waitcnt lgkmcnt(0)
	s_barrier
	s_waitcnt lgkmcnt(0)
	v_mfma_f32_16x16x32_bf16 v[124:127], v[160:163], v[192:195], v[124:127]
	v_mfma_f32_16x16x32_bf16 v[120:123], v[168:171], v[192:195], v[120:123]
	v_mfma_f32_16x16x32_bf16 v[108:111], v[160:163], v[200:203], v[108:111]
	v_mfma_f32_16x16x32_bf16 v[104:107], v[168:171], v[200:203], v[104:107]
	v_mfma_f32_16x16x32_bf16 v[92:95], v[160:163], v[208:211], v[92:95]
	v_mfma_f32_16x16x32_bf16 v[88:91], v[168:171], v[208:211], v[88:91]
	v_mfma_f32_16x16x32_bf16 v[76:79], v[160:163], v[216:219], v[76:79]
	v_mfma_f32_16x16x32_bf16 v[72:75], v[168:171], v[216:219], v[72:75]
	v_mfma_f32_16x16x32_bf16 v[124:127], v[164:167], v[196:199], v[124:127]
	v_mfma_f32_16x16x32_bf16 v[120:123], v[172:175], v[196:199], v[120:123]
	v_mfma_f32_16x16x32_bf16 v[108:111], v[164:167], v[204:207], v[108:111]
	v_mfma_f32_16x16x32_bf16 v[104:107], v[172:175], v[204:207], v[104:107]
	v_mfma_f32_16x16x32_bf16 v[92:95], v[164:167], v[212:215], v[92:95]
	v_mfma_f32_16x16x32_bf16 v[88:91], v[172:175], v[212:215], v[88:91]
	v_mfma_f32_16x16x32_bf16 v[76:79], v[164:167], v[220:223], v[76:79]
	v_mfma_f32_16x16x32_bf16 v[72:75], v[172:175], v[220:223], v[72:75]
	v_mfma_f32_16x16x32_bf16 v[116:119], v[176:179], v[192:195], v[116:119]
	v_mfma_f32_16x16x32_bf16 v[112:115], v[184:187], v[192:195], v[112:115]
	v_mfma_f32_16x16x32_bf16 v[100:103], v[176:179], v[200:203], v[100:103]
	v_mfma_f32_16x16x32_bf16 v[96:99], v[184:187], v[200:203], v[96:99]
	v_mfma_f32_16x16x32_bf16 v[84:87], v[176:179], v[208:211], v[84:87]
	v_mfma_f32_16x16x32_bf16 v[80:83], v[184:187], v[208:211], v[80:83]
	v_mfma_f32_16x16x32_bf16 v[68:71], v[176:179], v[216:219], v[68:71]
	v_mfma_f32_16x16x32_bf16 v[64:67], v[184:187], v[216:219], v[64:67]
	v_mfma_f32_16x16x32_bf16 v[116:119], v[180:183], v[196:199], v[116:119]
	v_mfma_f32_16x16x32_bf16 v[112:115], v[188:191], v[196:199], v[112:115]
	v_mfma_f32_16x16x32_bf16 v[100:103], v[180:183], v[204:207], v[100:103]
	v_mfma_f32_16x16x32_bf16 v[96:99], v[188:191], v[204:207], v[96:99]
	v_mfma_f32_16x16x32_bf16 v[84:87], v[180:183], v[212:215], v[84:87]
	v_mfma_f32_16x16x32_bf16 v[80:83], v[188:191], v[212:215], v[80:83]
	v_mfma_f32_16x16x32_bf16 v[68:71], v[180:183], v[220:223], v[68:71]
	v_mfma_f32_16x16x32_bf16 v[64:67], v[188:191], v[220:223], v[64:67]
	s_barrier
	s_add_i32 s42, s57, s39
	v_lshl_add_u64 v[148:149], s[46:47], 0, v[132:133]
	s_mov_b32 m0, s42
	ds_read_b128 v[192:195], v158 offset:16384
	ds_read_b128 v[196:199], v158 offset:17408
	ds_read_b128 v[200:203], v158 offset:18432
	ds_read_b128 v[204:207], v158 offset:19456
	ds_read_b128 v[208:211], v158 offset:20480
	ds_read_b128 v[212:215], v158 offset:21504
	ds_read_b128 v[216:219], v158 offset:22528
	ds_read_b128 v[220:223], v158 offset:23552
	global_load_lds_dwordx4 v[148:149], off
	s_add_i32 m0, s42, 0x2000
	s_add_u32 s42, s46, 0x80000
	v_lshl_add_u64 v[224:225], s[46:47], 0, v[128:129]
	s_addc_u32 s43, s47, 0
	s_add_i32 s64, s58, s39
	global_load_lds_dwordx4 v[224:225], off
	v_lshl_add_u64 v[226:227], s[42:43], 0, v[132:133]
	s_mov_b32 m0, s64
	v_lshl_add_u64 v[228:229], s[52:53], 0, v[130:131]
	global_load_lds_dwordx4 v[226:227], off
	v_lshl_add_u64 v[226:227], s[42:43], 0, v[128:129]
	s_add_i32 m0, s64, 0x2000
	s_nop 0
	global_load_lds_dwordx4 v[226:227], off
	v_lshl_add_u64 v[226:227], s[52:53], 0, v[134:135]
	s_mov_b32 m0, s31
	s_nop 0
	global_load_lds_dwordx4 v[226:227], off
	s_mov_b32 m0, s44
	s_nop 0
	global_load_lds_dwordx4 v[228:229], off
	s_waitcnt vmcnt(8)
	s_waitcnt lgkmcnt(0)
	s_barrier
	s_waitcnt lgkmcnt(0)
	v_mfma_f32_16x16x32_bf16 v[60:63], v[160:163], v[192:195], v[60:63]
	v_mfma_f32_16x16x32_bf16 v[56:59], v[168:171], v[192:195], v[56:59]
	v_mfma_f32_16x16x32_bf16 v[44:47], v[160:163], v[200:203], v[44:47]
	v_mfma_f32_16x16x32_bf16 v[40:43], v[168:171], v[200:203], v[40:43]
	v_mfma_f32_16x16x32_bf16 v[28:31], v[160:163], v[208:211], v[28:31]
	v_mfma_f32_16x16x32_bf16 v[24:27], v[168:171], v[208:211], v[24:27]
	v_mfma_f32_16x16x32_bf16 v[12:15], v[160:163], v[216:219], v[12:15]
	v_mfma_f32_16x16x32_bf16 v[8:11], v[168:171], v[216:219], v[8:11]
	v_mfma_f32_16x16x32_bf16 v[60:63], v[164:167], v[196:199], v[60:63]
	v_mfma_f32_16x16x32_bf16 v[56:59], v[172:175], v[196:199], v[56:59]
	v_mfma_f32_16x16x32_bf16 v[44:47], v[164:167], v[204:207], v[44:47]
	v_mfma_f32_16x16x32_bf16 v[40:43], v[172:175], v[204:207], v[40:43]
	v_mfma_f32_16x16x32_bf16 v[28:31], v[164:167], v[212:215], v[28:31]
	v_mfma_f32_16x16x32_bf16 v[24:27], v[172:175], v[212:215], v[24:27]
	v_mfma_f32_16x16x32_bf16 v[12:15], v[164:167], v[220:223], v[12:15]
	v_mfma_f32_16x16x32_bf16 v[8:11], v[172:175], v[220:223], v[8:11]
	v_mfma_f32_16x16x32_bf16 v[52:55], v[176:179], v[192:195], v[52:55]
	v_mfma_f32_16x16x32_bf16 v[48:51], v[184:187], v[192:195], v[48:51]
	v_mfma_f32_16x16x32_bf16 v[36:39], v[176:179], v[200:203], v[36:39]
	v_mfma_f32_16x16x32_bf16 v[32:35], v[184:187], v[200:203], v[32:35]
	v_mfma_f32_16x16x32_bf16 v[20:23], v[176:179], v[208:211], v[20:23]
	v_mfma_f32_16x16x32_bf16 v[16:19], v[184:187], v[208:211], v[16:19]
	v_mfma_f32_16x16x32_bf16 v[4:7], v[176:179], v[216:219], v[4:7]
	v_mfma_f32_16x16x32_bf16 v[0:3], v[184:187], v[216:219], v[0:3]
	v_mfma_f32_16x16x32_bf16 v[52:55], v[180:183], v[196:199], v[52:55]
	v_mfma_f32_16x16x32_bf16 v[48:51], v[188:191], v[196:199], v[48:51]
	v_mfma_f32_16x16x32_bf16 v[36:39], v[180:183], v[204:207], v[36:39]
	v_mfma_f32_16x16x32_bf16 v[32:35], v[188:191], v[204:207], v[32:35]
	v_mfma_f32_16x16x32_bf16 v[20:23], v[180:183], v[212:215], v[20:23]
	v_mfma_f32_16x16x32_bf16 v[16:19], v[188:191], v[212:215], v[16:19]
	v_mfma_f32_16x16x32_bf16 v[4:7], v[180:183], v[220:223], v[4:7]
	v_mfma_f32_16x16x32_bf16 v[0:3], v[188:191], v[220:223], v[0:3]
	s_barrier
	s_add_i32 s64, 0, 0x18000
	v_add_u32_e32 v159, s64, v151
	s_add_i32 s65, 0, 0x1c000
	ds_read_b128 v[160:163], v159
	ds_read_b128 v[164:167], v159 offset:1024
	ds_read_b128 v[168:171], v159 offset:2048
	ds_read_b128 v[172:175], v159 offset:3072
	v_add_u32_e32 v159, s65, v151
	ds_read_b128 v[176:179], v159
	ds_read_b128 v[180:183], v159 offset:1024
	ds_read_b128 v[184:187], v159 offset:2048
	ds_read_b128 v[188:191], v159 offset:3072
	s_add_u32 s42, s52, 0x80000
	s_addc_u32 s43, s53, 0
	s_mov_b32 m0, s45
	v_lshl_add_u64 v[230:231], s[42:43], 0, v[134:135]
	ds_read_b128 v[192:195], v158 offset:32768
	ds_read_b128 v[196:199], v158 offset:33792
	ds_read_b128 v[200:203], v158 offset:34816
	ds_read_b128 v[204:207], v158 offset:35840
	ds_read_b128 v[208:211], v158 offset:36864
	ds_read_b128 v[212:215], v158 offset:37888
	ds_read_b128 v[216:219], v158 offset:38912
	ds_read_b128 v[220:223], v158 offset:39936
	global_load_lds_dwordx4 v[230:231], off
	v_lshl_add_u64 v[230:231], s[42:43], 0, v[130:131]
	s_mov_b32 m0, s48
	s_nop 0
	global_load_lds_dwordx4 v[230:231], off
	s_waitcnt vmcnt(8)
	s_waitcnt lgkmcnt(0)
	s_barrier
	s_waitcnt lgkmcnt(0)
	v_mfma_f32_16x16x32_bf16 v[124:127], v[160:163], v[192:195], v[124:127]
	v_mfma_f32_16x16x32_bf16 v[120:123], v[168:171], v[192:195], v[120:123]
	v_mfma_f32_16x16x32_bf16 v[108:111], v[160:163], v[200:203], v[108:111]
	v_mfma_f32_16x16x32_bf16 v[104:107], v[168:171], v[200:203], v[104:107]
	v_mfma_f32_16x16x32_bf16 v[92:95], v[160:163], v[208:211], v[92:95]
	v_mfma_f32_16x16x32_bf16 v[88:91], v[168:171], v[208:211], v[88:91]
	v_mfma_f32_16x16x32_bf16 v[76:79], v[160:163], v[216:219], v[76:79]
	v_mfma_f32_16x16x32_bf16 v[72:75], v[168:171], v[216:219], v[72:75]
	v_mfma_f32_16x16x32_bf16 v[124:127], v[164:167], v[196:199], v[124:127]
	v_mfma_f32_16x16x32_bf16 v[120:123], v[172:175], v[196:199], v[120:123]
	v_mfma_f32_16x16x32_bf16 v[108:111], v[164:167], v[204:207], v[108:111]
	v_mfma_f32_16x16x32_bf16 v[104:107], v[172:175], v[204:207], v[104:107]
	v_mfma_f32_16x16x32_bf16 v[92:95], v[164:167], v[212:215], v[92:95]
	v_mfma_f32_16x16x32_bf16 v[88:91], v[172:175], v[212:215], v[88:91]
	v_mfma_f32_16x16x32_bf16 v[76:79], v[164:167], v[220:223], v[76:79]
	v_mfma_f32_16x16x32_bf16 v[72:75], v[172:175], v[220:223], v[72:75]
	v_mfma_f32_16x16x32_bf16 v[116:119], v[176:179], v[192:195], v[116:119]
	v_mfma_f32_16x16x32_bf16 v[112:115], v[184:187], v[192:195], v[112:115]
	v_mfma_f32_16x16x32_bf16 v[100:103], v[176:179], v[200:203], v[100:103]
	v_mfma_f32_16x16x32_bf16 v[96:99], v[184:187], v[200:203], v[96:99]
	v_mfma_f32_16x16x32_bf16 v[84:87], v[176:179], v[208:211], v[84:87]
	v_mfma_f32_16x16x32_bf16 v[80:83], v[184:187], v[208:211], v[80:83]
	v_mfma_f32_16x16x32_bf16 v[68:71], v[176:179], v[216:219], v[68:71]
	v_mfma_f32_16x16x32_bf16 v[64:67], v[184:187], v[216:219], v[64:67]
	v_mfma_f32_16x16x32_bf16 v[116:119], v[180:183], v[196:199], v[116:119]
	v_mfma_f32_16x16x32_bf16 v[112:115], v[188:191], v[196:199], v[112:115]
	v_mfma_f32_16x16x32_bf16 v[100:103], v[180:183], v[204:207], v[100:103]
	v_mfma_f32_16x16x32_bf16 v[96:99], v[188:191], v[204:207], v[96:99]
	v_mfma_f32_16x16x32_bf16 v[84:87], v[180:183], v[212:215], v[84:87]
	v_mfma_f32_16x16x32_bf16 v[80:83], v[188:191], v[212:215], v[80:83]
	v_mfma_f32_16x16x32_bf16 v[68:71], v[180:183], v[220:223], v[68:71]
	v_mfma_f32_16x16x32_bf16 v[64:67], v[188:191], v[220:223], v[64:67]
	s_barrier
	s_add_i32 s42, s64, s39
	v_lshl_add_u64 v[148:149], v[148:149], 0, s[16:17]
	s_mov_b32 m0, s42
	ds_read_b128 v[192:195], v158 offset:49152
	ds_read_b128 v[196:199], v158 offset:50176
	ds_read_b128 v[200:203], v158 offset:51200
	ds_read_b128 v[204:207], v158 offset:52224
	ds_read_b128 v[208:211], v158 offset:53248
	ds_read_b128 v[212:215], v158 offset:54272
	ds_read_b128 v[216:219], v158 offset:55296
	ds_read_b128 v[220:223], v158 offset:56320
	global_load_lds_dwordx4 v[148:149], off
	s_add_i32 m0, s42, 0x2000
	s_add_u32 s42, s46, 0x80080
	v_lshl_add_u64 v[148:149], v[224:225], 0, s[16:17]
	s_addc_u32 s43, s47, 0
	s_add_i32 s46, s65, s39
	global_load_lds_dwordx4 v[148:149], off
	v_lshl_add_u64 v[148:149], s[42:43], 0, v[132:133]
	s_mov_b32 m0, s46
	s_nop 0
	global_load_lds_dwordx4 v[148:149], off
	v_lshl_add_u64 v[148:149], s[42:43], 0, v[128:129]
	s_add_i32 m0, s46, 0x2000
	s_nop 0
	global_load_lds_dwordx4 v[148:149], off
	v_lshl_add_u64 v[148:149], v[226:227], 0, s[16:17]
	s_mov_b32 m0, s49
	s_nop 0
	global_load_lds_dwordx4 v[148:149], off
	v_lshl_add_u64 v[148:149], v[228:229], 0, s[16:17]
	s_mov_b32 m0, s54
	s_nop 0
	global_load_lds_dwordx4 v[148:149], off
	s_waitcnt vmcnt(8)
	s_waitcnt lgkmcnt(0)
	s_barrier
	s_waitcnt lgkmcnt(0)
	v_mfma_f32_16x16x32_bf16 v[60:63], v[160:163], v[192:195], v[60:63]
	v_mfma_f32_16x16x32_bf16 v[56:59], v[168:171], v[192:195], v[56:59]
	v_mfma_f32_16x16x32_bf16 v[44:47], v[160:163], v[200:203], v[44:47]
	v_mfma_f32_16x16x32_bf16 v[40:43], v[168:171], v[200:203], v[40:43]
	v_mfma_f32_16x16x32_bf16 v[28:31], v[160:163], v[208:211], v[28:31]
	v_mfma_f32_16x16x32_bf16 v[24:27], v[168:171], v[208:211], v[24:27]
	v_mfma_f32_16x16x32_bf16 v[12:15], v[160:163], v[216:219], v[12:15]
	v_mfma_f32_16x16x32_bf16 v[8:11], v[168:171], v[216:219], v[8:11]
	v_mfma_f32_16x16x32_bf16 v[60:63], v[164:167], v[196:199], v[60:63]
	v_mfma_f32_16x16x32_bf16 v[56:59], v[172:175], v[196:199], v[56:59]
	v_mfma_f32_16x16x32_bf16 v[44:47], v[164:167], v[204:207], v[44:47]
	v_mfma_f32_16x16x32_bf16 v[40:43], v[172:175], v[204:207], v[40:43]
	v_mfma_f32_16x16x32_bf16 v[28:31], v[164:167], v[212:215], v[28:31]
	v_mfma_f32_16x16x32_bf16 v[24:27], v[172:175], v[212:215], v[24:27]
	v_mfma_f32_16x16x32_bf16 v[12:15], v[164:167], v[220:223], v[12:15]
	v_mfma_f32_16x16x32_bf16 v[8:11], v[172:175], v[220:223], v[8:11]
	v_mfma_f32_16x16x32_bf16 v[52:55], v[176:179], v[192:195], v[52:55]
	v_mfma_f32_16x16x32_bf16 v[48:51], v[184:187], v[192:195], v[48:51]
	v_mfma_f32_16x16x32_bf16 v[36:39], v[176:179], v[200:203], v[36:39]
	v_mfma_f32_16x16x32_bf16 v[32:35], v[184:187], v[200:203], v[32:35]
	v_mfma_f32_16x16x32_bf16 v[20:23], v[176:179], v[208:211], v[20:23]
	v_mfma_f32_16x16x32_bf16 v[16:19], v[184:187], v[208:211], v[16:19]
	v_mfma_f32_16x16x32_bf16 v[4:7], v[176:179], v[216:219], v[4:7]
	v_mfma_f32_16x16x32_bf16 v[0:3], v[184:187], v[216:219], v[0:3]
	v_mfma_f32_16x16x32_bf16 v[52:55], v[180:183], v[196:199], v[52:55]
	v_mfma_f32_16x16x32_bf16 v[48:51], v[188:191], v[196:199], v[48:51]
	v_mfma_f32_16x16x32_bf16 v[36:39], v[180:183], v[204:207], v[36:39]
	v_mfma_f32_16x16x32_bf16 v[32:35], v[188:191], v[204:207], v[32:35]
	v_mfma_f32_16x16x32_bf16 v[20:23], v[180:183], v[212:215], v[20:23]
	v_mfma_f32_16x16x32_bf16 v[16:19], v[188:191], v[212:215], v[16:19]
	v_mfma_f32_16x16x32_bf16 v[4:7], v[180:183], v[220:223], v[4:7]
	v_mfma_f32_16x16x32_bf16 v[0:3], v[188:191], v[220:223], v[0:3]
	s_barrier
	s_add_i32 s63, s63, 2
	v_lshl_add_u64 v[144:145], v[144:145], 0, s[20:21]
	v_lshl_add_u64 v[146:147], v[146:147], 0, s[20:21]
	s_cbranch_vccz .LBB0_2375
	s_and_b64 vcc, exec, s[18:19]
	s_cbranch_vccz .LBB0_2378
	s_barrier

.LBB0_2466:
	s_add_i32 s26, s34, s61
	s_cmpk_lt_u32 s26, 0x58
	s_cselect_b32 s27, 0, 0xffffffa8
	s_add_i32 s28, s26, s27
	s_cmpk_lt_i32 s28, 0x56
	s_cselect_b32 s29, 0, 0xffffffa8
	ds_read_b128 v[140:143], v147
	ds_read_b128 v[150:153], v147 offset:1024
	ds_read_b128 v[154:157], v147 offset:2048
	ds_read_b128 v[158:161], v147 offset:3072
	ds_read_b128 v[162:165], v148
	ds_read_b128 v[166:169], v148 offset:1024
	ds_read_b128 v[170:173], v148 offset:2048
	ds_read_b128 v[174:177], v148 offset:3072
	s_add_i32 s27, s27, s29
	s_add_i32 s26, s26, s27
	s_add_i32 s26, s26, 2
	s_add_i32 s42, s28, 1
	s_ashr_i32 s27, s26, 31
	s_ashr_i32 s43, s42, 31
	s_lshl_b64 s[26:27], s[26:27], 7
	s_add_u32 s28, s24, s26
	s_addc_u32 s29, s25, s27
	s_add_u32 s26, s22, s26
	s_addc_u32 s27, s23, s27
	s_cmpk_eq_i32 s61, 0x56
	s_cselect_b32 s29, s58, s29
	s_cselect_b32 s28, s57, s28
	s_cselect_b32 s27, s60, s27
	s_cselect_b32 s26, s59, s26
	s_lshl_b64 s[42:43], s[42:43], 7
	s_add_u32 s42, s55, s42
	s_addc_u32 s43, s56, s43
	v_lshl_add_u64 v[210:211], s[42:43], 0, v[128:129]
	s_add_i32 m0, s39, 0xc000
	ds_read_b128 v[178:181], v149
	ds_read_b128 v[182:185], v149 offset:1024
	ds_read_b128 v[186:189], v149 offset:2048
	ds_read_b128 v[190:193], v149 offset:3072
	ds_read_b128 v[194:197], v149 offset:4096
	ds_read_b128 v[198:201], v149 offset:5120
	ds_read_b128 v[202:205], v149 offset:6144
	ds_read_b128 v[206:209], v149 offset:7168
	global_load_lds_dwordx4 v[210:211], off
	v_lshl_add_u64 v[210:211], s[42:43], 0, v[132:133]
	s_add_i32 m0, s39, 0xe000
	s_nop 0
	global_load_lds_dwordx4 v[210:211], off
	s_waitcnt vmcnt(8)
	s_waitcnt lgkmcnt(0)
	s_barrier
	s_waitcnt lgkmcnt(0)
	v_mfma_f32_16x16x32_bf16 v[124:127], v[140:143], v[178:181], v[124:127]
	v_mfma_f32_16x16x32_bf16 v[120:123], v[154:157], v[178:181], v[120:123]
	v_mfma_f32_16x16x32_bf16 v[116:119], v[140:143], v[186:189], v[116:119]
	v_mfma_f32_16x16x32_bf16 v[108:111], v[154:157], v[186:189], v[108:111]
	v_mfma_f32_16x16x32_bf16 v[100:103], v[140:143], v[194:197], v[100:103]
	v_mfma_f32_16x16x32_bf16 v[92:95], v[154:157], v[194:197], v[92:95]
	v_mfma_f32_16x16x32_bf16 v[84:87], v[140:143], v[202:205], v[84:87]
	v_mfma_f32_16x16x32_bf16 v[76:79], v[154:157], v[202:205], v[76:79]
	v_mfma_f32_16x16x32_bf16 v[124:127], v[150:153], v[182:185], v[124:127]
	v_mfma_f32_16x16x32_bf16 v[120:123], v[158:161], v[182:185], v[120:123]
	v_mfma_f32_16x16x32_bf16 v[116:119], v[150:153], v[190:193], v[116:119]
	v_mfma_f32_16x16x32_bf16 v[108:111], v[158:161], v[190:193], v[108:111]
	v_mfma_f32_16x16x32_bf16 v[100:103], v[150:153], v[198:201], v[100:103]
	v_mfma_f32_16x16x32_bf16 v[92:95], v[158:161], v[198:201], v[92:95]
	v_mfma_f32_16x16x32_bf16 v[84:87], v[150:153], v[206:209], v[84:87]
	v_mfma_f32_16x16x32_bf16 v[76:79], v[158:161], v[206:209], v[76:79]
	v_mfma_f32_16x16x32_bf16 v[112:115], v[162:165], v[178:181], v[112:115]
	v_mfma_f32_16x16x32_bf16 v[104:107], v[170:173], v[178:181], v[104:107]
	v_mfma_f32_16x16x32_bf16 v[96:99], v[162:165], v[186:189], v[96:99]
	v_mfma_f32_16x16x32_bf16 v[88:91], v[170:173], v[186:189], v[88:91]
	v_mfma_f32_16x16x32_bf16 v[80:83], v[162:165], v[194:197], v[80:83]
	v_mfma_f32_16x16x32_bf16 v[72:75], v[170:173], v[194:197], v[72:75]
	v_mfma_f32_16x16x32_bf16 v[68:71], v[162:165], v[202:205], v[68:71]
	v_mfma_f32_16x16x32_bf16 v[64:67], v[170:173], v[202:205], v[64:67]
	v_mfma_f32_16x16x32_bf16 v[112:115], v[166:169], v[182:185], v[112:115]
	v_mfma_f32_16x16x32_bf16 v[104:107], v[174:177], v[182:185], v[104:107]
	v_mfma_f32_16x16x32_bf16 v[96:99], v[166:169], v[190:193], v[96:99]
	v_mfma_f32_16x16x32_bf16 v[88:91], v[174:177], v[190:193], v[88:91]
	v_mfma_f32_16x16x32_bf16 v[80:83], v[166:169], v[198:201], v[80:83]
	v_mfma_f32_16x16x32_bf16 v[72:75], v[174:177], v[198:201], v[72:75]
	v_mfma_f32_16x16x32_bf16 v[68:71], v[166:169], v[206:209], v[68:71]
	v_mfma_f32_16x16x32_bf16 v[64:67], v[174:177], v[206:209], v[64:67]
	s_barrier
	s_add_i32 s42, s49, s35
	v_lshl_add_u64 v[210:211], s[26:27], 0, v[130:131]
	s_mov_b32 m0, s42
	ds_read_b128 v[178:181], v149 offset:16384
	ds_read_b128 v[182:185], v149 offset:17408
	ds_read_b128 v[186:189], v149 offset:18432
	ds_read_b128 v[190:193], v149 offset:19456
	ds_read_b128 v[194:197], v149 offset:20480
	ds_read_b128 v[198:201], v149 offset:21504
	ds_read_b128 v[202:205], v149 offset:22528
	ds_read_b128 v[206:209], v149 offset:23552
	global_load_lds_dwordx4 v[210:211], off
	s_add_i32 m0, s42, 0x2000
	s_add_u32 s42, s26, 0x160000
	v_lshl_add_u64 v[212:213], s[26:27], 0, v[134:135]
	s_addc_u32 s43, s27, 0
	s_add_i32 s62, s50, s35
	global_load_lds_dwordx4 v[212:213], off
	v_lshl_add_u64 v[214:215], s[42:43], 0, v[130:131]
	s_mov_b32 m0, s62
	v_lshl_add_u64 v[216:217], s[28:29], 0, v[132:133]
	global_load_lds_dwordx4 v[214:215], off
	v_lshl_add_u64 v[214:215], s[42:43], 0, v[134:135]
	s_add_i32 m0, s62, 0x2000
	s_nop 0
	global_load_lds_dwordx4 v[214:215], off
	v_lshl_add_u64 v[214:215], s[28:29], 0, v[128:129]
	s_mov_b32 m0, s39
	s_nop 0
	global_load_lds_dwordx4 v[214:215], off
	s_mov_b32 m0, s40
	s_nop 0
	global_load_lds_dwordx4 v[216:217], off
	s_waitcnt vmcnt(8)
	s_waitcnt lgkmcnt(0)
	s_barrier
	s_waitcnt lgkmcnt(0)
	v_mfma_f32_16x16x32_bf16 v[60:63], v[140:143], v[178:181], v[60:63]
	v_mfma_f32_16x16x32_bf16 v[56:59], v[154:157], v[178:181], v[56:59]
	v_mfma_f32_16x16x32_bf16 v[52:55], v[140:143], v[186:189], v[52:55]
	v_mfma_f32_16x16x32_bf16 v[44:47], v[154:157], v[186:189], v[44:47]
	v_mfma_f32_16x16x32_bf16 v[36:39], v[140:143], v[194:197], v[36:39]
	v_mfma_f32_16x16x32_bf16 v[28:31], v[154:157], v[194:197], v[28:31]
	v_mfma_f32_16x16x32_bf16 v[20:23], v[140:143], v[202:205], v[20:23]
	v_mfma_f32_16x16x32_bf16 v[12:15], v[154:157], v[202:205], v[12:15]
	v_mfma_f32_16x16x32_bf16 v[60:63], v[150:153], v[182:185], v[60:63]
	v_mfma_f32_16x16x32_bf16 v[56:59], v[158:161], v[182:185], v[56:59]
	v_mfma_f32_16x16x32_bf16 v[52:55], v[150:153], v[190:193], v[52:55]
	v_mfma_f32_16x16x32_bf16 v[44:47], v[158:161], v[190:193], v[44:47]
	v_mfma_f32_16x16x32_bf16 v[36:39], v[150:153], v[198:201], v[36:39]
	v_mfma_f32_16x16x32_bf16 v[28:31], v[158:161], v[198:201], v[28:31]
	v_mfma_f32_16x16x32_bf16 v[20:23], v[150:153], v[206:209], v[20:23]
	v_mfma_f32_16x16x32_bf16 v[12:15], v[158:161], v[206:209], v[12:15]
	v_mfma_f32_16x16x32_bf16 v[48:51], v[162:165], v[178:181], v[48:51]
	v_mfma_f32_16x16x32_bf16 v[40:43], v[170:173], v[178:181], v[40:43]
	v_mfma_f32_16x16x32_bf16 v[32:35], v[162:165], v[186:189], v[32:35]
	v_mfma_f32_16x16x32_bf16 v[24:27], v[170:173], v[186:189], v[24:27]
	v_mfma_f32_16x16x32_bf16 v[16:19], v[162:165], v[194:197], v[16:19]
	v_mfma_f32_16x16x32_bf16 v[8:11], v[170:173], v[194:197], v[8:11]
	v_mfma_f32_16x16x32_bf16 v[4:7], v[162:165], v[202:205], v[4:7]
	v_mfma_f32_16x16x32_bf16 v[0:3], v[170:173], v[202:205], v[0:3]
	v_mfma_f32_16x16x32_bf16 v[48:51], v[166:169], v[182:185], v[48:51]
	v_mfma_f32_16x16x32_bf16 v[40:43], v[174:177], v[182:185], v[40:43]
	v_mfma_f32_16x16x32_bf16 v[32:35], v[166:169], v[190:193], v[32:35]
	v_mfma_f32_16x16x32_bf16 v[24:27], v[174:177], v[190:193], v[24:27]
	v_mfma_f32_16x16x32_bf16 v[16:19], v[166:169], v[198:201], v[16:19]
	v_mfma_f32_16x16x32_bf16 v[8:11], v[174:177], v[198:201], v[8:11]
	v_mfma_f32_16x16x32_bf16 v[4:7], v[166:169], v[206:209], v[4:7]
	v_mfma_f32_16x16x32_bf16 v[0:3], v[174:177], v[206:209], v[0:3]
	s_barrier
	s_add_i32 s42, 0, 0x18000
	s_add_i32 s43, 0, 0x1c000
	v_add_u32_e32 v158, s42, v145
	v_add_u32_e32 v174, s43, v145
	ds_read_b128 v[140:143], v158
	ds_read_b128 v[150:153], v158 offset:1024
	ds_read_b128 v[154:157], v158 offset:2048
	ds_read_b128 v[158:161], v158 offset:3072
	ds_read_b128 v[162:165], v174
	ds_read_b128 v[166:169], v174 offset:1024
	ds_read_b128 v[170:173], v174 offset:2048
	ds_read_b128 v[174:177], v174 offset:3072
	s_add_u32 s28, s28, 0x160000
	s_addc_u32 s29, s29, 0
	s_mov_b32 m0, s41
	v_lshl_add_u64 v[218:219], s[28:29], 0, v[128:129]
	ds_read_b128 v[178:181], v149 offset:32768
	ds_read_b128 v[182:185], v149 offset:33792
	ds_read_b128 v[186:189], v149 offset:34816
	ds_read_b128 v[190:193], v149 offset:35840
	ds_read_b128 v[194:197], v149 offset:36864
	ds_read_b128 v[198:201], v149 offset:37888
	ds_read_b128 v[202:205], v149 offset:38912
	ds_read_b128 v[206:209], v149 offset:39936
	global_load_lds_dwordx4 v[218:219], off
	v_lshl_add_u64 v[218:219], s[28:29], 0, v[132:133]
	s_mov_b32 m0, s44
	s_nop 0
	global_load_lds_dwordx4 v[218:219], off
	s_waitcnt vmcnt(8)
	s_waitcnt lgkmcnt(0)
	s_barrier
	s_waitcnt lgkmcnt(0)
	v_mfma_f32_16x16x32_bf16 v[124:127], v[140:143], v[178:181], v[124:127]
	v_mfma_f32_16x16x32_bf16 v[120:123], v[154:157], v[178:181], v[120:123]
	v_mfma_f32_16x16x32_bf16 v[116:119], v[140:143], v[186:189], v[116:119]
	v_mfma_f32_16x16x32_bf16 v[108:111], v[154:157], v[186:189], v[108:111]
	v_mfma_f32_16x16x32_bf16 v[100:103], v[140:143], v[194:197], v[100:103]
	v_mfma_f32_16x16x32_bf16 v[92:95], v[154:157], v[194:197], v[92:95]
	v_mfma_f32_16x16x32_bf16 v[84:87], v[140:143], v[202:205], v[84:87]
	v_mfma_f32_16x16x32_bf16 v[76:79], v[154:157], v[202:205], v[76:79]
	v_mfma_f32_16x16x32_bf16 v[124:127], v[150:153], v[182:185], v[124:127]
	v_mfma_f32_16x16x32_bf16 v[120:123], v[158:161], v[182:185], v[120:123]
	v_mfma_f32_16x16x32_bf16 v[116:119], v[150:153], v[190:193], v[116:119]
	v_mfma_f32_16x16x32_bf16 v[108:111], v[158:161], v[190:193], v[108:111]
	v_mfma_f32_16x16x32_bf16 v[100:103], v[150:153], v[198:201], v[100:103]
	v_mfma_f32_16x16x32_bf16 v[92:95], v[158:161], v[198:201], v[92:95]
	v_mfma_f32_16x16x32_bf16 v[84:87], v[150:153], v[206:209], v[84:87]
	v_mfma_f32_16x16x32_bf16 v[76:79], v[158:161], v[206:209], v[76:79]
	v_mfma_f32_16x16x32_bf16 v[112:115], v[162:165], v[178:181], v[112:115]
	v_mfma_f32_16x16x32_bf16 v[104:107], v[170:173], v[178:181], v[104:107]
	v_mfma_f32_16x16x32_bf16 v[96:99], v[162:165], v[186:189], v[96:99]
	v_mfma_f32_16x16x32_bf16 v[88:91], v[170:173], v[186:189], v[88:91]
	v_mfma_f32_16x16x32_bf16 v[80:83], v[162:165], v[194:197], v[80:83]
	v_mfma_f32_16x16x32_bf16 v[72:75], v[170:173], v[194:197], v[72:75]
	v_mfma_f32_16x16x32_bf16 v[68:71], v[162:165], v[202:205], v[68:71]
	v_mfma_f32_16x16x32_bf16 v[64:67], v[170:173], v[202:205], v[64:67]
	v_mfma_f32_16x16x32_bf16 v[112:115], v[166:169], v[182:185], v[112:115]
	v_mfma_f32_16x16x32_bf16 v[104:107], v[174:177], v[182:185], v[104:107]
	v_mfma_f32_16x16x32_bf16 v[96:99], v[166:169], v[190:193], v[96:99]
	v_mfma_f32_16x16x32_bf16 v[88:91], v[174:177], v[190:193], v[88:91]
	v_mfma_f32_16x16x32_bf16 v[80:83], v[166:169], v[198:201], v[80:83]
	v_mfma_f32_16x16x32_bf16 v[72:75], v[174:177], v[198:201], v[72:75]
	v_mfma_f32_16x16x32_bf16 v[68:71], v[166:169], v[206:209], v[68:71]
	v_mfma_f32_16x16x32_bf16 v[64:67], v[174:177], v[206:209], v[64:67]
	s_barrier
	s_add_i32 s28, s42, s35
	v_lshl_add_u64 v[210:211], v[210:211], 0, s[16:17]
	s_mov_b32 m0, s28
	ds_read_b128 v[178:181], v149 offset:49152
	ds_read_b128 v[182:185], v149 offset:50176
	ds_read_b128 v[186:189], v149 offset:51200
	ds_read_b128 v[190:193], v149 offset:52224
	ds_read_b128 v[194:197], v149 offset:53248
	ds_read_b128 v[198:201], v149 offset:54272
	ds_read_b128 v[202:205], v149 offset:55296
	ds_read_b128 v[206:209], v149 offset:56320
	global_load_lds_dwordx4 v[210:211], off
	s_add_i32 m0, s28, 0x2000
	s_add_u32 s26, s26, 0x160080
	v_lshl_add_u64 v[210:211], v[212:213], 0, s[16:17]
	s_addc_u32 s27, s27, 0
	s_add_i32 s28, s43, s35
	global_load_lds_dwordx4 v[210:211], off
	v_lshl_add_u64 v[210:211], s[26:27], 0, v[130:131]
	s_mov_b32 m0, s28
	s_nop 0
	global_load_lds_dwordx4 v[210:211], off
	v_lshl_add_u64 v[210:211], s[26:27], 0, v[134:135]
	s_add_i32 m0, s28, 0x2000
	s_nop 0
	global_load_lds_dwordx4 v[210:211], off
	v_lshl_add_u64 v[210:211], v[214:215], 0, s[16:17]
	s_mov_b32 m0, s46
	s_nop 0
	global_load_lds_dwordx4 v[210:211], off
	v_lshl_add_u64 v[210:211], v[216:217], 0, s[16:17]
	s_mov_b32 m0, s47
	s_nop 0
	global_load_lds_dwordx4 v[210:211], off
	s_waitcnt vmcnt(8)
	s_waitcnt lgkmcnt(0)
	s_barrier
	s_waitcnt lgkmcnt(0)
	v_mfma_f32_16x16x32_bf16 v[60:63], v[140:143], v[178:181], v[60:63]
	v_mfma_f32_16x16x32_bf16 v[56:59], v[154:157], v[178:181], v[56:59]
	v_mfma_f32_16x16x32_bf16 v[52:55], v[140:143], v[186:189], v[52:55]
	v_mfma_f32_16x16x32_bf16 v[44:47], v[154:157], v[186:189], v[44:47]
	v_mfma_f32_16x16x32_bf16 v[36:39], v[140:143], v[194:197], v[36:39]
	v_mfma_f32_16x16x32_bf16 v[28:31], v[154:157], v[194:197], v[28:31]
	v_mfma_f32_16x16x32_bf16 v[20:23], v[140:143], v[202:205], v[20:23]
	v_mfma_f32_16x16x32_bf16 v[12:15], v[154:157], v[202:205], v[12:15]
	v_mfma_f32_16x16x32_bf16 v[60:63], v[150:153], v[182:185], v[60:63]
	v_mfma_f32_16x16x32_bf16 v[56:59], v[158:161], v[182:185], v[56:59]
	v_mfma_f32_16x16x32_bf16 v[52:55], v[150:153], v[190:193], v[52:55]
	v_mfma_f32_16x16x32_bf16 v[44:47], v[158:161], v[190:193], v[44:47]
	v_mfma_f32_16x16x32_bf16 v[36:39], v[150:153], v[198:201], v[36:39]
	v_mfma_f32_16x16x32_bf16 v[28:31], v[158:161], v[198:201], v[28:31]
	v_mfma_f32_16x16x32_bf16 v[20:23], v[150:153], v[206:209], v[20:23]
	v_mfma_f32_16x16x32_bf16 v[12:15], v[158:161], v[206:209], v[12:15]
	v_mfma_f32_16x16x32_bf16 v[48:51], v[162:165], v[178:181], v[48:51]
	v_mfma_f32_16x16x32_bf16 v[40:43], v[170:173], v[178:181], v[40:43]
	v_mfma_f32_16x16x32_bf16 v[32:35], v[162:165], v[186:189], v[32:35]
	v_mfma_f32_16x16x32_bf16 v[24:27], v[170:173], v[186:189], v[24:27]
	v_mfma_f32_16x16x32_bf16 v[16:19], v[162:165], v[194:197], v[16:19]
	v_mfma_f32_16x16x32_bf16 v[8:11], v[170:173], v[194:197], v[8:11]
	v_mfma_f32_16x16x32_bf16 v[4:7], v[162:165], v[202:205], v[4:7]
	v_mfma_f32_16x16x32_bf16 v[0:3], v[170:173], v[202:205], v[0:3]
	v_mfma_f32_16x16x32_bf16 v[48:51], v[166:169], v[182:185], v[48:51]
	v_mfma_f32_16x16x32_bf16 v[40:43], v[174:177], v[182:185], v[40:43]
	v_mfma_f32_16x16x32_bf16 v[32:35], v[166:169], v[190:193], v[32:35]
	v_mfma_f32_16x16x32_bf16 v[24:27], v[174:177], v[190:193], v[24:27]
	v_mfma_f32_16x16x32_bf16 v[16:19], v[166:169], v[198:201], v[16:19]
	v_mfma_f32_16x16x32_bf16 v[8:11], v[174:177], v[198:201], v[8:11]
	v_mfma_f32_16x16x32_bf16 v[4:7], v[166:169], v[206:209], v[4:7]
	v_mfma_f32_16x16x32_bf16 v[0:3], v[174:177], v[206:209], v[0:3]
	s_barrier
	s_add_i32 s26, s61, 2
	s_cmpk_gt_u32 s61, 0x55
	s_mov_b32 s61, s26
	s_cbranch_scc0 .LBB0_2466
	s_and_b64 vcc, exec, s[18:19]
	s_cbranch_vccz .LBB0_2469
	s_barrier
